# norm phase body rewritten (all 8 rows' loads in flight, DPP reductions); adaLN GEMV job: all 64 weight loads issued up front
# speedup vs baseline: 1.1032x; 1.0108x over previous
.LBB0_66:
	v_add_co_u32_e32 v42, vcc, 0x1000, v16
	s_nop 1
	v_addc_co_u32_e32 v43, vcc, 0, v17, vcc
	global_load_dwordx4 v[44:47], v[16:17], off offset:0
	global_load_dwordx4 v[76:79], v[42:43], off offset:0
	global_load_dwordx4 v[48:51], v[16:17], off offset:16
	global_load_dwordx4 v[80:83], v[42:43], off offset:16
	global_load_dwordx4 v[52:55], v[16:17], off offset:32
	global_load_dwordx4 v[84:87], v[42:43], off offset:32
	global_load_dwordx4 v[56:59], v[16:17], off offset:48
	global_load_dwordx4 v[88:91], v[42:43], off offset:48
	global_load_dwordx4 v[60:63], v[16:17], off offset:64
	global_load_dwordx4 v[92:95], v[42:43], off offset:64
	global_load_dwordx4 v[64:67], v[16:17], off offset:80
	global_load_dwordx4 v[96:99], v[42:43], off offset:80
	global_load_dwordx4 v[68:71], v[16:17], off offset:96
	global_load_dwordx4 v[100:103], v[42:43], off offset:96
	global_load_dwordx4 v[72:75], v[16:17], off offset:112
	global_load_dwordx4 v[104:107], v[42:43], off offset:112
	global_load_dword v108, v[4:5], off
	v_add_co_u32_e32 v4, vcc, 0x3000, v4
	s_nop 1
	v_addc_co_u32_e32 v5, vcc, 0, v5, vcc
	global_load_dword v109, v[4:5], off
	v_add_co_u32_e32 v4, vcc, 0x3000, v4
	s_nop 1
	v_addc_co_u32_e32 v5, vcc, 0, v5, vcc
	global_load_dword v110, v[4:5], off
	v_add_co_u32_e32 v4, vcc, 0x3000, v4
	s_nop 1
	v_addc_co_u32_e32 v5, vcc, 0, v5, vcc
	global_load_dword v111, v[4:5], off
	v_add_co_u32_e32 v4, vcc, 0x3000, v4
	s_nop 1
	v_addc_co_u32_e32 v5, vcc, 0, v5, vcc
	global_load_dword v112, v[4:5], off
	v_add_co_u32_e32 v4, vcc, 0x3000, v4
	s_nop 1
	v_addc_co_u32_e32 v5, vcc, 0, v5, vcc
	global_load_dword v113, v[4:5], off
	v_add_co_u32_e32 v4, vcc, 0x3000, v4
	s_nop 1
	v_addc_co_u32_e32 v5, vcc, 0, v5, vcc
	global_load_dword v114, v[4:5], off
	v_add_co_u32_e32 v4, vcc, 0x3000, v4
	s_nop 1
	v_addc_co_u32_e32 v5, vcc, 0, v5, vcc
	global_load_dword v115, v[4:5], off
	v_add_co_u32_e32 v4, vcc, 0x3000, v4
	s_nop 1
	v_addc_co_u32_e32 v5, vcc, 0, v5, vcc
	global_load_dword v116, v[4:5], off
	v_add_co_u32_e32 v4, vcc, 0x3000, v4
	s_nop 1
	v_addc_co_u32_e32 v5, vcc, 0, v5, vcc
	global_load_dword v117, v[4:5], off
	v_add_co_u32_e32 v4, vcc, 0x3000, v4
	s_nop 1
	v_addc_co_u32_e32 v5, vcc, 0, v5, vcc
	global_load_dword v118, v[4:5], off
	v_add_co_u32_e32 v4, vcc, 0x3000, v4
	s_nop 1
	v_addc_co_u32_e32 v5, vcc, 0, v5, vcc
	global_load_dword v119, v[4:5], off
	v_add_co_u32_e32 v4, vcc, 0x3000, v4
	s_nop 1
	v_addc_co_u32_e32 v5, vcc, 0, v5, vcc
	global_load_dword v120, v[4:5], off
	v_add_co_u32_e32 v4, vcc, 0x3000, v4
	s_nop 1
	v_addc_co_u32_e32 v5, vcc, 0, v5, vcc
	global_load_dword v121, v[4:5], off
	v_add_co_u32_e32 v4, vcc, 0x3000, v4
	s_nop 1
	v_addc_co_u32_e32 v5, vcc, 0, v5, vcc
	global_load_dword v122, v[4:5], off
	v_add_co_u32_e32 v4, vcc, 0x3000, v4
	s_nop 1
	v_addc_co_u32_e32 v5, vcc, 0, v5, vcc
	global_load_dword v123, v[4:5], off
	v_add_co_u32_e32 v4, vcc, 0x3000, v4
	s_nop 1
	v_addc_co_u32_e32 v5, vcc, 0, v5, vcc
	global_load_dword v124, v[4:5], off
	v_add_co_u32_e32 v4, vcc, 0x3000, v4
	s_nop 1
	v_addc_co_u32_e32 v5, vcc, 0, v5, vcc
	global_load_dword v125, v[4:5], off
	v_add_co_u32_e32 v4, vcc, 0x3000, v4
	s_nop 1
	v_addc_co_u32_e32 v5, vcc, 0, v5, vcc
	global_load_dword v126, v[4:5], off
	v_add_co_u32_e32 v4, vcc, 0x3000, v4
	s_nop 1
	v_addc_co_u32_e32 v5, vcc, 0, v5, vcc
	global_load_dword v127, v[4:5], off
	v_add_co_u32_e32 v4, vcc, 0x3000, v4
	s_nop 1
	v_addc_co_u32_e32 v5, vcc, 0, v5, vcc
	global_load_dword v128, v[4:5], off
	v_add_co_u32_e32 v4, vcc, 0x3000, v4
	s_nop 1
	v_addc_co_u32_e32 v5, vcc, 0, v5, vcc
	global_load_dword v129, v[4:5], off
	v_add_co_u32_e32 v4, vcc, 0x3000, v4
	s_nop 1
	v_addc_co_u32_e32 v5, vcc, 0, v5, vcc
	global_load_dword v130, v[4:5], off
	v_add_co_u32_e32 v4, vcc, 0x3000, v4
	s_nop 1
	v_addc_co_u32_e32 v5, vcc, 0, v5, vcc
	global_load_dword v131, v[4:5], off
	v_add_co_u32_e32 v4, vcc, 0x3000, v4
	s_nop 1
	v_addc_co_u32_e32 v5, vcc, 0, v5, vcc
	global_load_dword v132, v[4:5], off
	v_add_co_u32_e32 v4, vcc, 0x3000, v4
	s_nop 1
	v_addc_co_u32_e32 v5, vcc, 0, v5, vcc
	global_load_dword v133, v[4:5], off
	v_add_co_u32_e32 v4, vcc, 0x3000, v4
	s_nop 1
	v_addc_co_u32_e32 v5, vcc, 0, v5, vcc
	global_load_dword v134, v[4:5], off
	v_add_co_u32_e32 v4, vcc, 0x3000, v4
	s_nop 1
	v_addc_co_u32_e32 v5, vcc, 0, v5, vcc
	global_load_dword v135, v[4:5], off
	v_add_co_u32_e32 v4, vcc, 0x3000, v4
	s_nop 1
	v_addc_co_u32_e32 v5, vcc, 0, v5, vcc
	global_load_dword v136, v[4:5], off
	v_add_co_u32_e32 v4, vcc, 0x3000, v4
	s_nop 1
	v_addc_co_u32_e32 v5, vcc, 0, v5, vcc
	global_load_dword v137, v[4:5], off
	v_add_co_u32_e32 v4, vcc, 0x3000, v4
	s_nop 1
	v_addc_co_u32_e32 v5, vcc, 0, v5, vcc
	global_load_dword v138, v[4:5], off
	v_add_co_u32_e32 v4, vcc, 0x3000, v4
	s_nop 1
	v_addc_co_u32_e32 v5, vcc, 0, v5, vcc
	global_load_dword v139, v[4:5], off
	v_add_co_u32_e32 v4, vcc, 0x3000, v4
	s_nop 1
	v_addc_co_u32_e32 v5, vcc, 0, v5, vcc
	global_load_dwordx4 v[146:149], v[16:17], off offset:128
	global_load_dwordx4 v[178:181], v[42:43], off offset:128
	global_load_dwordx4 v[150:153], v[16:17], off offset:144
	global_load_dwordx4 v[182:185], v[42:43], off offset:144
	global_load_dwordx4 v[154:157], v[16:17], off offset:160
	global_load_dwordx4 v[186:189], v[42:43], off offset:160
	global_load_dwordx4 v[158:161], v[16:17], off offset:176
	global_load_dwordx4 v[190:193], v[42:43], off offset:176
	global_load_dwordx4 v[162:165], v[16:17], off offset:192
	global_load_dwordx4 v[194:197], v[42:43], off offset:192
	global_load_dwordx4 v[166:169], v[16:17], off offset:208
	global_load_dwordx4 v[198:201], v[42:43], off offset:208
	global_load_dwordx4 v[170:173], v[16:17], off offset:224
	global_load_dwordx4 v[202:205], v[42:43], off offset:224
	global_load_dwordx4 v[174:177], v[16:17], off offset:240
	global_load_dwordx4 v[206:209], v[42:43], off offset:240
	global_load_dword v210, v[4:5], off
	v_add_co_u32_e32 v4, vcc, 0x3000, v4
	s_nop 1
	v_addc_co_u32_e32 v5, vcc, 0, v5, vcc
	global_load_dword v211, v[4:5], off
	v_add_co_u32_e32 v4, vcc, 0x3000, v4
	s_nop 1
	v_addc_co_u32_e32 v5, vcc, 0, v5, vcc
	global_load_dword v212, v[4:5], off
	v_add_co_u32_e32 v4, vcc, 0x3000, v4
	s_nop 1
	v_addc_co_u32_e32 v5, vcc, 0, v5, vcc
	global_load_dword v213, v[4:5], off
	v_add_co_u32_e32 v4, vcc, 0x3000, v4
	s_nop 1
	v_addc_co_u32_e32 v5, vcc, 0, v5, vcc
	global_load_dword v214, v[4:5], off
	v_add_co_u32_e32 v4, vcc, 0x3000, v4
	s_nop 1
	v_addc_co_u32_e32 v5, vcc, 0, v5, vcc
	global_load_dword v215, v[4:5], off
	v_add_co_u32_e32 v4, vcc, 0x3000, v4
	s_nop 1
	v_addc_co_u32_e32 v5, vcc, 0, v5, vcc
	global_load_dword v216, v[4:5], off
	v_add_co_u32_e32 v4, vcc, 0x3000, v4
	s_nop 1
	v_addc_co_u32_e32 v5, vcc, 0, v5, vcc
	global_load_dword v217, v[4:5], off
	v_add_co_u32_e32 v4, vcc, 0x3000, v4
	s_nop 1
	v_addc_co_u32_e32 v5, vcc, 0, v5, vcc
	global_load_dword v218, v[4:5], off
	v_add_co_u32_e32 v4, vcc, 0x3000, v4
	s_nop 1
	v_addc_co_u32_e32 v5, vcc, 0, v5, vcc
	global_load_dword v219, v[4:5], off
	v_add_co_u32_e32 v4, vcc, 0x3000, v4
	s_nop 1
	v_addc_co_u32_e32 v5, vcc, 0, v5, vcc
	global_load_dword v220, v[4:5], off
	v_add_co_u32_e32 v4, vcc, 0x3000, v4
	s_nop 1
	v_addc_co_u32_e32 v5, vcc, 0, v5, vcc
	global_load_dword v221, v[4:5], off
	v_add_co_u32_e32 v4, vcc, 0x3000, v4
	s_nop 1
	v_addc_co_u32_e32 v5, vcc, 0, v5, vcc
	global_load_dword v222, v[4:5], off
	v_add_co_u32_e32 v4, vcc, 0x3000, v4
	s_nop 1
	v_addc_co_u32_e32 v5, vcc, 0, v5, vcc
	global_load_dword v223, v[4:5], off
	v_add_co_u32_e32 v4, vcc, 0x3000, v4
	s_nop 1
	v_addc_co_u32_e32 v5, vcc, 0, v5, vcc
	global_load_dword v224, v[4:5], off
	v_add_co_u32_e32 v4, vcc, 0x3000, v4
	s_nop 1
	v_addc_co_u32_e32 v5, vcc, 0, v5, vcc
	global_load_dword v225, v[4:5], off
	v_add_co_u32_e32 v4, vcc, 0x3000, v4
	s_nop 1
	v_addc_co_u32_e32 v5, vcc, 0, v5, vcc
	global_load_dword v226, v[4:5], off
	v_add_co_u32_e32 v4, vcc, 0x3000, v4
	s_nop 1
	v_addc_co_u32_e32 v5, vcc, 0, v5, vcc
	global_load_dword v227, v[4:5], off
	v_add_co_u32_e32 v4, vcc, 0x3000, v4
	s_nop 1
	v_addc_co_u32_e32 v5, vcc, 0, v5, vcc
	global_load_dword v228, v[4:5], off
	v_add_co_u32_e32 v4, vcc, 0x3000, v4
	s_nop 1
	v_addc_co_u32_e32 v5, vcc, 0, v5, vcc
	global_load_dword v229, v[4:5], off
	v_add_co_u32_e32 v4, vcc, 0x3000, v4
	s_nop 1
	v_addc_co_u32_e32 v5, vcc, 0, v5, vcc
	global_load_dword v230, v[4:5], off
	v_add_co_u32_e32 v4, vcc, 0x3000, v4
	s_nop 1
	v_addc_co_u32_e32 v5, vcc, 0, v5, vcc
	global_load_dword v231, v[4:5], off
	v_add_co_u32_e32 v4, vcc, 0x3000, v4
	s_nop 1
	v_addc_co_u32_e32 v5, vcc, 0, v5, vcc
	global_load_dword v232, v[4:5], off
	v_add_co_u32_e32 v4, vcc, 0x3000, v4
	s_nop 1
	v_addc_co_u32_e32 v5, vcc, 0, v5, vcc
	global_load_dword v233, v[4:5], off
	v_add_co_u32_e32 v4, vcc, 0x3000, v4
	s_nop 1
	v_addc_co_u32_e32 v5, vcc, 0, v5, vcc
	global_load_dword v234, v[4:5], off
	v_add_co_u32_e32 v4, vcc, 0x3000, v4
	s_nop 1
	v_addc_co_u32_e32 v5, vcc, 0, v5, vcc
	global_load_dword v235, v[4:5], off
	v_add_co_u32_e32 v4, vcc, 0x3000, v4
	s_nop 1
	v_addc_co_u32_e32 v5, vcc, 0, v5, vcc
	global_load_dword v236, v[4:5], off
	v_add_co_u32_e32 v4, vcc, 0x3000, v4
	s_nop 1
	v_addc_co_u32_e32 v5, vcc, 0, v5, vcc
	global_load_dword v238, v[4:5], off
	v_add_co_u32_e32 v4, vcc, 0x3000, v4
	s_nop 1
	v_addc_co_u32_e32 v5, vcc, 0, v5, vcc
	global_load_dword v239, v[4:5], off
	v_add_co_u32_e32 v4, vcc, 0x3000, v4
	s_nop 1
	v_addc_co_u32_e32 v5, vcc, 0, v5, vcc
	global_load_dword v240, v[4:5], off
	v_add_co_u32_e32 v4, vcc, 0x3000, v4
	s_nop 1
	v_addc_co_u32_e32 v5, vcc, 0, v5, vcc
	global_load_dword v241, v[4:5], off
	v_add_co_u32_e32 v4, vcc, 0x3000, v4
	s_nop 1
	v_addc_co_u32_e32 v5, vcc, 0, v5, vcc
	global_load_dword v242, v[4:5], off
	v_add_co_u32_e32 v4, vcc, 0x3000, v4
	s_nop 1
	v_addc_co_u32_e32 v5, vcc, 0, v5, vcc
	s_waitcnt vmcnt(48)
	v_mul_f32_e32 v8, 0xbfb8aa3b, v44
	v_mul_f32_e32 v9, 0xbfb8aa3b, v45
	v_mul_f32_e32 v10, 0xbfb8aa3b, v46
	v_mul_f32_e32 v18, 0xbfb8aa3b, v47
	v_mul_f32_e32 v19, 0xbfb8aa3b, v76
	v_mul_f32_e32 v24, 0xbfb8aa3b, v77
	v_mul_f32_e32 v25, 0xbfb8aa3b, v78
	v_mul_f32_e32 v26, 0xbfb8aa3b, v79
	v_exp_f32_e32 v8, v8
	v_exp_f32_e32 v9, v9
	v_exp_f32_e32 v10, v10
	v_exp_f32_e32 v18, v18
	v_exp_f32_e32 v19, v19
	v_exp_f32_e32 v24, v24
	v_exp_f32_e32 v25, v25
	v_exp_f32_e32 v26, v26
	v_add_f32_e32 v8, 1.0, v8
	v_add_f32_e32 v9, 1.0, v9
	v_add_f32_e32 v10, 1.0, v10
	v_add_f32_e32 v18, 1.0, v18
	v_add_f32_e32 v19, 1.0, v19
	v_add_f32_e32 v24, 1.0, v24
	v_add_f32_e32 v25, 1.0, v25
	v_add_f32_e32 v26, 1.0, v26
	v_rcp_f32_e32 v8, v8
	v_rcp_f32_e32 v9, v9
	v_rcp_f32_e32 v10, v10
	v_rcp_f32_e32 v18, v18
	v_rcp_f32_e32 v19, v19
	v_rcp_f32_e32 v24, v24
	v_rcp_f32_e32 v25, v25
	v_rcp_f32_e32 v26, v26
	v_mul_f32_e32 v8, v44, v8
	v_mul_f32_e32 v9, v45, v9
	v_mul_f32_e32 v10, v46, v10
	v_mul_f32_e32 v18, v47, v18
	v_mul_f32_e32 v19, v76, v19
	v_mul_f32_e32 v24, v77, v24
	v_mul_f32_e32 v25, v78, v25
	v_mul_f32_e32 v26, v79, v26
	v_fma_f32 v6, v108, v8, v6
	v_fma_f32 v7, v108, v19, v7
	v_fma_f32 v6, v109, v9, v6
	v_fma_f32 v7, v109, v24, v7
	v_fma_f32 v6, v110, v10, v6
	v_fma_f32 v7, v110, v25, v7
	v_fma_f32 v6, v111, v18, v6
	v_fma_f32 v7, v111, v26, v7
	v_mul_f32_e32 v8, 0xbfb8aa3b, v48
	v_mul_f32_e32 v9, 0xbfb8aa3b, v49
	v_mul_f32_e32 v10, 0xbfb8aa3b, v50
	v_mul_f32_e32 v18, 0xbfb8aa3b, v51
	v_mul_f32_e32 v19, 0xbfb8aa3b, v80
	v_mul_f32_e32 v24, 0xbfb8aa3b, v81
	v_mul_f32_e32 v25, 0xbfb8aa3b, v82
	v_mul_f32_e32 v26, 0xbfb8aa3b, v83
	v_exp_f32_e32 v8, v8
	v_exp_f32_e32 v9, v9
	v_exp_f32_e32 v10, v10
	v_exp_f32_e32 v18, v18
	v_exp_f32_e32 v19, v19
	v_exp_f32_e32 v24, v24
	v_exp_f32_e32 v25, v25
	v_exp_f32_e32 v26, v26
	v_add_f32_e32 v8, 1.0, v8
	v_add_f32_e32 v9, 1.0, v9
	v_add_f32_e32 v10, 1.0, v10
	v_add_f32_e32 v18, 1.0, v18
	v_add_f32_e32 v19, 1.0, v19
	v_add_f32_e32 v24, 1.0, v24
	v_add_f32_e32 v25, 1.0, v25
	v_add_f32_e32 v26, 1.0, v26
	v_rcp_f32_e32 v8, v8
	v_rcp_f32_e32 v9, v9
	v_rcp_f32_e32 v10, v10
	v_rcp_f32_e32 v18, v18
	v_rcp_f32_e32 v19, v19
	v_rcp_f32_e32 v24, v24
	v_rcp_f32_e32 v25, v25
	v_rcp_f32_e32 v26, v26
	v_mul_f32_e32 v8, v48, v8
	v_mul_f32_e32 v9, v49, v9
	v_mul_f32_e32 v10, v50, v10
	v_mul_f32_e32 v18, v51, v18
	v_mul_f32_e32 v19, v80, v19
	v_mul_f32_e32 v24, v81, v24
	v_mul_f32_e32 v25, v82, v25
	v_mul_f32_e32 v26, v83, v26
	v_fma_f32 v6, v112, v8, v6
	v_fma_f32 v7, v112, v19, v7
	v_fma_f32 v6, v113, v9, v6
	v_fma_f32 v7, v113, v24, v7
	v_fma_f32 v6, v114, v10, v6
	v_fma_f32 v7, v114, v25, v7
	v_fma_f32 v6, v115, v18, v6
	v_fma_f32 v7, v115, v26, v7
	v_mul_f32_e32 v8, 0xbfb8aa3b, v52
	v_mul_f32_e32 v9, 0xbfb8aa3b, v53
	v_mul_f32_e32 v10, 0xbfb8aa3b, v54
	v_mul_f32_e32 v18, 0xbfb8aa3b, v55
	v_mul_f32_e32 v19, 0xbfb8aa3b, v84
	v_mul_f32_e32 v24, 0xbfb8aa3b, v85
	v_mul_f32_e32 v25, 0xbfb8aa3b, v86
	v_mul_f32_e32 v26, 0xbfb8aa3b, v87
	v_exp_f32_e32 v8, v8
	v_exp_f32_e32 v9, v9
	v_exp_f32_e32 v10, v10
	v_exp_f32_e32 v18, v18
	v_exp_f32_e32 v19, v19
	v_exp_f32_e32 v24, v24
	v_exp_f32_e32 v25, v25
	v_exp_f32_e32 v26, v26
	v_add_f32_e32 v8, 1.0, v8
	v_add_f32_e32 v9, 1.0, v9
	v_add_f32_e32 v10, 1.0, v10
	v_add_f32_e32 v18, 1.0, v18
	v_add_f32_e32 v19, 1.0, v19
	v_add_f32_e32 v24, 1.0, v24
	v_add_f32_e32 v25, 1.0, v25
	v_add_f32_e32 v26, 1.0, v26
	v_rcp_f32_e32 v8, v8
	v_rcp_f32_e32 v9, v9
	v_rcp_f32_e32 v10, v10
	v_rcp_f32_e32 v18, v18
	v_rcp_f32_e32 v19, v19
	v_rcp_f32_e32 v24, v24
	v_rcp_f32_e32 v25, v25
	v_rcp_f32_e32 v26, v26
	v_mul_f32_e32 v8, v52, v8
	v_mul_f32_e32 v9, v53, v9
	v_mul_f32_e32 v10, v54, v10
	v_mul_f32_e32 v18, v55, v18
	v_mul_f32_e32 v19, v84, v19
	v_mul_f32_e32 v24, v85, v24
	v_mul_f32_e32 v25, v86, v25
	v_mul_f32_e32 v26, v87, v26
	v_fma_f32 v6, v116, v8, v6
	v_fma_f32 v7, v116, v19, v7
	v_fma_f32 v6, v117, v9, v6
	v_fma_f32 v7, v117, v24, v7
	v_fma_f32 v6, v118, v10, v6
	v_fma_f32 v7, v118, v25, v7
	v_fma_f32 v6, v119, v18, v6
	v_fma_f32 v7, v119, v26, v7
	v_mul_f32_e32 v8, 0xbfb8aa3b, v56
	v_mul_f32_e32 v9, 0xbfb8aa3b, v57
	v_mul_f32_e32 v10, 0xbfb8aa3b, v58
	v_mul_f32_e32 v18, 0xbfb8aa3b, v59
	v_mul_f32_e32 v19, 0xbfb8aa3b, v88
	v_mul_f32_e32 v24, 0xbfb8aa3b, v89
	v_mul_f32_e32 v25, 0xbfb8aa3b, v90
	v_mul_f32_e32 v26, 0xbfb8aa3b, v91
	v_exp_f32_e32 v8, v8
	v_exp_f32_e32 v9, v9
	v_exp_f32_e32 v10, v10
	v_exp_f32_e32 v18, v18
	v_exp_f32_e32 v19, v19
	v_exp_f32_e32 v24, v24
	v_exp_f32_e32 v25, v25
	v_exp_f32_e32 v26, v26
	v_add_f32_e32 v8, 1.0, v8
	v_add_f32_e32 v9, 1.0, v9
	v_add_f32_e32 v10, 1.0, v10
	v_add_f32_e32 v18, 1.0, v18
	v_add_f32_e32 v19, 1.0, v19
	v_add_f32_e32 v24, 1.0, v24
	v_add_f32_e32 v25, 1.0, v25
	v_add_f32_e32 v26, 1.0, v26
	v_rcp_f32_e32 v8, v8
	v_rcp_f32_e32 v9, v9
	v_rcp_f32_e32 v10, v10
	v_rcp_f32_e32 v18, v18
	v_rcp_f32_e32 v19, v19
	v_rcp_f32_e32 v24, v24
	v_rcp_f32_e32 v25, v25
	v_rcp_f32_e32 v26, v26
	v_mul_f32_e32 v8, v56, v8
	v_mul_f32_e32 v9, v57, v9
	v_mul_f32_e32 v10, v58, v10
	v_mul_f32_e32 v18, v59, v18
	v_mul_f32_e32 v19, v88, v19
	v_mul_f32_e32 v24, v89, v24
	v_mul_f32_e32 v25, v90, v25
	v_mul_f32_e32 v26, v91, v26
	v_fma_f32 v6, v120, v8, v6
	v_fma_f32 v7, v120, v19, v7
	v_fma_f32 v6, v121, v9, v6
	v_fma_f32 v7, v121, v24, v7
	v_fma_f32 v6, v122, v10, v6
	v_fma_f32 v7, v122, v25, v7
	v_fma_f32 v6, v123, v18, v6
	v_fma_f32 v7, v123, v26, v7
	v_mul_f32_e32 v8, 0xbfb8aa3b, v60
	v_mul_f32_e32 v9, 0xbfb8aa3b, v61
	v_mul_f32_e32 v10, 0xbfb8aa3b, v62
	v_mul_f32_e32 v18, 0xbfb8aa3b, v63
	v_mul_f32_e32 v19, 0xbfb8aa3b, v92
	v_mul_f32_e32 v24, 0xbfb8aa3b, v93
	v_mul_f32_e32 v25, 0xbfb8aa3b, v94
	v_mul_f32_e32 v26, 0xbfb8aa3b, v95
	v_exp_f32_e32 v8, v8
	v_exp_f32_e32 v9, v9
	v_exp_f32_e32 v10, v10
	v_exp_f32_e32 v18, v18
	v_exp_f32_e32 v19, v19
	v_exp_f32_e32 v24, v24
	v_exp_f32_e32 v25, v25
	v_exp_f32_e32 v26, v26
	v_add_f32_e32 v8, 1.0, v8
	v_add_f32_e32 v9, 1.0, v9
	v_add_f32_e32 v10, 1.0, v10
	v_add_f32_e32 v18, 1.0, v18
	v_add_f32_e32 v19, 1.0, v19
	v_add_f32_e32 v24, 1.0, v24
	v_add_f32_e32 v25, 1.0, v25
	v_add_f32_e32 v26, 1.0, v26
	v_rcp_f32_e32 v8, v8
	v_rcp_f32_e32 v9, v9
	v_rcp_f32_e32 v10, v10
	v_rcp_f32_e32 v18, v18
	v_rcp_f32_e32 v19, v19
	v_rcp_f32_e32 v24, v24
	v_rcp_f32_e32 v25, v25
	v_rcp_f32_e32 v26, v26
	v_mul_f32_e32 v8, v60, v8
	v_mul_f32_e32 v9, v61, v9
	v_mul_f32_e32 v10, v62, v10
	v_mul_f32_e32 v18, v63, v18
	v_mul_f32_e32 v19, v92, v19
	v_mul_f32_e32 v24, v93, v24
	v_mul_f32_e32 v25, v94, v25
	v_mul_f32_e32 v26, v95, v26
	v_fma_f32 v6, v124, v8, v6
	v_fma_f32 v7, v124, v19, v7
	v_fma_f32 v6, v125, v9, v6
	v_fma_f32 v7, v125, v24, v7
	v_fma_f32 v6, v126, v10, v6
	v_fma_f32 v7, v126, v25, v7
	v_fma_f32 v6, v127, v18, v6
	v_fma_f32 v7, v127, v26, v7
	v_mul_f32_e32 v8, 0xbfb8aa3b, v64
	v_mul_f32_e32 v9, 0xbfb8aa3b, v65
	v_mul_f32_e32 v10, 0xbfb8aa3b, v66
	v_mul_f32_e32 v18, 0xbfb8aa3b, v67
	v_mul_f32_e32 v19, 0xbfb8aa3b, v96
	v_mul_f32_e32 v24, 0xbfb8aa3b, v97
	v_mul_f32_e32 v25, 0xbfb8aa3b, v98
	v_mul_f32_e32 v26, 0xbfb8aa3b, v99
	v_exp_f32_e32 v8, v8
	v_exp_f32_e32 v9, v9
	v_exp_f32_e32 v10, v10
	v_exp_f32_e32 v18, v18
	v_exp_f32_e32 v19, v19
	v_exp_f32_e32 v24, v24
	v_exp_f32_e32 v25, v25
	v_exp_f32_e32 v26, v26
	v_add_f32_e32 v8, 1.0, v8
	v_add_f32_e32 v9, 1.0, v9
	v_add_f32_e32 v10, 1.0, v10
	v_add_f32_e32 v18, 1.0, v18
	v_add_f32_e32 v19, 1.0, v19
	v_add_f32_e32 v24, 1.0, v24
	v_add_f32_e32 v25, 1.0, v25
	v_add_f32_e32 v26, 1.0, v26
	v_rcp_f32_e32 v8, v8
	v_rcp_f32_e32 v9, v9
	v_rcp_f32_e32 v10, v10
	v_rcp_f32_e32 v18, v18
	v_rcp_f32_e32 v19, v19
	v_rcp_f32_e32 v24, v24
	v_rcp_f32_e32 v25, v25
	v_rcp_f32_e32 v26, v26
	v_mul_f32_e32 v8, v64, v8
	v_mul_f32_e32 v9, v65, v9
	v_mul_f32_e32 v10, v66, v10
	v_mul_f32_e32 v18, v67, v18
	v_mul_f32_e32 v19, v96, v19
	v_mul_f32_e32 v24, v97, v24
	v_mul_f32_e32 v25, v98, v25
	v_mul_f32_e32 v26, v99, v26
	v_fma_f32 v6, v128, v8, v6
	v_fma_f32 v7, v128, v19, v7
	v_fma_f32 v6, v129, v9, v6
	v_fma_f32 v7, v129, v24, v7
	v_fma_f32 v6, v130, v10, v6
	v_fma_f32 v7, v130, v25, v7
	v_fma_f32 v6, v131, v18, v6
	v_fma_f32 v7, v131, v26, v7
	v_mul_f32_e32 v8, 0xbfb8aa3b, v68
	v_mul_f32_e32 v9, 0xbfb8aa3b, v69
	v_mul_f32_e32 v10, 0xbfb8aa3b, v70
	v_mul_f32_e32 v18, 0xbfb8aa3b, v71
	v_mul_f32_e32 v19, 0xbfb8aa3b, v100
	v_mul_f32_e32 v24, 0xbfb8aa3b, v101
	v_mul_f32_e32 v25, 0xbfb8aa3b, v102
	v_mul_f32_e32 v26, 0xbfb8aa3b, v103
	v_exp_f32_e32 v8, v8
	v_exp_f32_e32 v9, v9
	v_exp_f32_e32 v10, v10
	v_exp_f32_e32 v18, v18
	v_exp_f32_e32 v19, v19
	v_exp_f32_e32 v24, v24
	v_exp_f32_e32 v25, v25
	v_exp_f32_e32 v26, v26
	v_add_f32_e32 v8, 1.0, v8
	v_add_f32_e32 v9, 1.0, v9
	v_add_f32_e32 v10, 1.0, v10
	v_add_f32_e32 v18, 1.0, v18
	v_add_f32_e32 v19, 1.0, v19
	v_add_f32_e32 v24, 1.0, v24
	v_add_f32_e32 v25, 1.0, v25
	v_add_f32_e32 v26, 1.0, v26
	v_rcp_f32_e32 v8, v8
	v_rcp_f32_e32 v9, v9
	v_rcp_f32_e32 v10, v10
	v_rcp_f32_e32 v18, v18
	v_rcp_f32_e32 v19, v19
	v_rcp_f32_e32 v24, v24
	v_rcp_f32_e32 v25, v25
	v_rcp_f32_e32 v26, v26
	v_mul_f32_e32 v8, v68, v8
	v_mul_f32_e32 v9, v69, v9
	v_mul_f32_e32 v10, v70, v10
	v_mul_f32_e32 v18, v71, v18
	v_mul_f32_e32 v19, v100, v19
	v_mul_f32_e32 v24, v101, v24
	v_mul_f32_e32 v25, v102, v25
	v_mul_f32_e32 v26, v103, v26
	v_fma_f32 v6, v132, v8, v6
	v_fma_f32 v7, v132, v19, v7
	v_fma_f32 v6, v133, v9, v6
	v_fma_f32 v7, v133, v24, v7
	v_fma_f32 v6, v134, v10, v6
	v_fma_f32 v7, v134, v25, v7
	v_fma_f32 v6, v135, v18, v6
	v_fma_f32 v7, v135, v26, v7
	v_mul_f32_e32 v8, 0xbfb8aa3b, v72
	v_mul_f32_e32 v9, 0xbfb8aa3b, v73
	v_mul_f32_e32 v10, 0xbfb8aa3b, v74
	v_mul_f32_e32 v18, 0xbfb8aa3b, v75
	v_mul_f32_e32 v19, 0xbfb8aa3b, v104
	v_mul_f32_e32 v24, 0xbfb8aa3b, v105
	v_mul_f32_e32 v25, 0xbfb8aa3b, v106
	v_mul_f32_e32 v26, 0xbfb8aa3b, v107
	v_exp_f32_e32 v8, v8
	v_exp_f32_e32 v9, v9
	v_exp_f32_e32 v10, v10
	v_exp_f32_e32 v18, v18
	v_exp_f32_e32 v19, v19
	v_exp_f32_e32 v24, v24
	v_exp_f32_e32 v25, v25
	v_exp_f32_e32 v26, v26
	v_add_f32_e32 v8, 1.0, v8
	v_add_f32_e32 v9, 1.0, v9
	v_add_f32_e32 v10, 1.0, v10
	v_add_f32_e32 v18, 1.0, v18
	v_add_f32_e32 v19, 1.0, v19
	v_add_f32_e32 v24, 1.0, v24
	v_add_f32_e32 v25, 1.0, v25
	v_add_f32_e32 v26, 1.0, v26
	v_rcp_f32_e32 v8, v8
	v_rcp_f32_e32 v9, v9
	v_rcp_f32_e32 v10, v10
	v_rcp_f32_e32 v18, v18
	v_rcp_f32_e32 v19, v19
	v_rcp_f32_e32 v24, v24
	v_rcp_f32_e32 v25, v25
	v_rcp_f32_e32 v26, v26
	v_mul_f32_e32 v8, v72, v8
	v_mul_f32_e32 v9, v73, v9
	v_mul_f32_e32 v10, v74, v10
	v_mul_f32_e32 v18, v75, v18
	v_mul_f32_e32 v19, v104, v19
	v_mul_f32_e32 v24, v105, v24
	v_mul_f32_e32 v25, v106, v25
	v_mul_f32_e32 v26, v107, v26
	v_fma_f32 v6, v136, v8, v6
	v_fma_f32 v7, v136, v19, v7
	v_fma_f32 v6, v137, v9, v6
	v_fma_f32 v7, v137, v24, v7
	v_fma_f32 v6, v138, v10, v6
	v_fma_f32 v7, v138, v25, v7
	v_fma_f32 v6, v139, v18, v6
	v_fma_f32 v7, v139, v26, v7
	s_waitcnt vmcnt(0)
	v_mul_f32_e32 v8, 0xbfb8aa3b, v146
	v_mul_f32_e32 v9, 0xbfb8aa3b, v147
	v_mul_f32_e32 v10, 0xbfb8aa3b, v148
	v_mul_f32_e32 v18, 0xbfb8aa3b, v149
	v_mul_f32_e32 v19, 0xbfb8aa3b, v178
	v_mul_f32_e32 v24, 0xbfb8aa3b, v179
	v_mul_f32_e32 v25, 0xbfb8aa3b, v180
	v_mul_f32_e32 v26, 0xbfb8aa3b, v181
	v_exp_f32_e32 v8, v8
	v_exp_f32_e32 v9, v9
	v_exp_f32_e32 v10, v10
	v_exp_f32_e32 v18, v18
	v_exp_f32_e32 v19, v19
	v_exp_f32_e32 v24, v24
	v_exp_f32_e32 v25, v25
	v_exp_f32_e32 v26, v26
	v_add_f32_e32 v8, 1.0, v8
	v_add_f32_e32 v9, 1.0, v9
	v_add_f32_e32 v10, 1.0, v10
	v_add_f32_e32 v18, 1.0, v18
	v_add_f32_e32 v19, 1.0, v19
	v_add_f32_e32 v24, 1.0, v24
	v_add_f32_e32 v25, 1.0, v25
	v_add_f32_e32 v26, 1.0, v26
	v_rcp_f32_e32 v8, v8
	v_rcp_f32_e32 v9, v9
	v_rcp_f32_e32 v10, v10
	v_rcp_f32_e32 v18, v18
	v_rcp_f32_e32 v19, v19
	v_rcp_f32_e32 v24, v24
	v_rcp_f32_e32 v25, v25
	v_rcp_f32_e32 v26, v26
	v_mul_f32_e32 v8, v146, v8
	v_mul_f32_e32 v9, v147, v9
	v_mul_f32_e32 v10, v148, v10
	v_mul_f32_e32 v18, v149, v18
	v_mul_f32_e32 v19, v178, v19
	v_mul_f32_e32 v24, v179, v24
	v_mul_f32_e32 v25, v180, v25
	v_mul_f32_e32 v26, v181, v26
	v_fma_f32 v6, v210, v8, v6
	v_fma_f32 v7, v210, v19, v7
	v_fma_f32 v6, v211, v9, v6
	v_fma_f32 v7, v211, v24, v7
	v_fma_f32 v6, v212, v10, v6
	v_fma_f32 v7, v212, v25, v7
	v_fma_f32 v6, v213, v18, v6
	v_fma_f32 v7, v213, v26, v7
	v_mul_f32_e32 v8, 0xbfb8aa3b, v150
	v_mul_f32_e32 v9, 0xbfb8aa3b, v151
	v_mul_f32_e32 v10, 0xbfb8aa3b, v152
	v_mul_f32_e32 v18, 0xbfb8aa3b, v153
	v_mul_f32_e32 v19, 0xbfb8aa3b, v182
	v_mul_f32_e32 v24, 0xbfb8aa3b, v183
	v_mul_f32_e32 v25, 0xbfb8aa3b, v184
	v_mul_f32_e32 v26, 0xbfb8aa3b, v185
	v_exp_f32_e32 v8, v8
	v_exp_f32_e32 v9, v9
	v_exp_f32_e32 v10, v10
	v_exp_f32_e32 v18, v18
	v_exp_f32_e32 v19, v19
	v_exp_f32_e32 v24, v24
	v_exp_f32_e32 v25, v25
	v_exp_f32_e32 v26, v26
	v_add_f32_e32 v8, 1.0, v8
	v_add_f32_e32 v9, 1.0, v9
	v_add_f32_e32 v10, 1.0, v10
	v_add_f32_e32 v18, 1.0, v18
	v_add_f32_e32 v19, 1.0, v19
	v_add_f32_e32 v24, 1.0, v24
	v_add_f32_e32 v25, 1.0, v25
	v_add_f32_e32 v26, 1.0, v26
	v_rcp_f32_e32 v8, v8
	v_rcp_f32_e32 v9, v9
	v_rcp_f32_e32 v10, v10
	v_rcp_f32_e32 v18, v18
	v_rcp_f32_e32 v19, v19
	v_rcp_f32_e32 v24, v24
	v_rcp_f32_e32 v25, v25
	v_rcp_f32_e32 v26, v26
	v_mul_f32_e32 v8, v150, v8
	v_mul_f32_e32 v9, v151, v9
	v_mul_f32_e32 v10, v152, v10
	v_mul_f32_e32 v18, v153, v18
	v_mul_f32_e32 v19, v182, v19
	v_mul_f32_e32 v24, v183, v24
	v_mul_f32_e32 v25, v184, v25
	v_mul_f32_e32 v26, v185, v26
	v_fma_f32 v6, v214, v8, v6
	v_fma_f32 v7, v214, v19, v7
	v_fma_f32 v6, v215, v9, v6
	v_fma_f32 v7, v215, v24, v7
	v_fma_f32 v6, v216, v10, v6
	v_fma_f32 v7, v216, v25, v7
	v_fma_f32 v6, v217, v18, v6
	v_fma_f32 v7, v217, v26, v7
	v_mul_f32_e32 v8, 0xbfb8aa3b, v154
	v_mul_f32_e32 v9, 0xbfb8aa3b, v155
	v_mul_f32_e32 v10, 0xbfb8aa3b, v156
	v_mul_f32_e32 v18, 0xbfb8aa3b, v157
	v_mul_f32_e32 v19, 0xbfb8aa3b, v186
	v_mul_f32_e32 v24, 0xbfb8aa3b, v187
	v_mul_f32_e32 v25, 0xbfb8aa3b, v188
	v_mul_f32_e32 v26, 0xbfb8aa3b, v189
	v_exp_f32_e32 v8, v8
	v_exp_f32_e32 v9, v9
	v_exp_f32_e32 v10, v10
	v_exp_f32_e32 v18, v18
	v_exp_f32_e32 v19, v19
	v_exp_f32_e32 v24, v24
	v_exp_f32_e32 v25, v25
	v_exp_f32_e32 v26, v26
	v_add_f32_e32 v8, 1.0, v8
	v_add_f32_e32 v9, 1.0, v9
	v_add_f32_e32 v10, 1.0, v10
	v_add_f32_e32 v18, 1.0, v18
	v_add_f32_e32 v19, 1.0, v19
	v_add_f32_e32 v24, 1.0, v24
	v_add_f32_e32 v25, 1.0, v25
	v_add_f32_e32 v26, 1.0, v26
	v_rcp_f32_e32 v8, v8
	v_rcp_f32_e32 v9, v9
	v_rcp_f32_e32 v10, v10
	v_rcp_f32_e32 v18, v18
	v_rcp_f32_e32 v19, v19
	v_rcp_f32_e32 v24, v24
	v_rcp_f32_e32 v25, v25
	v_rcp_f32_e32 v26, v26
	v_mul_f32_e32 v8, v154, v8
	v_mul_f32_e32 v9, v155, v9
	v_mul_f32_e32 v10, v156, v10
	v_mul_f32_e32 v18, v157, v18
	v_mul_f32_e32 v19, v186, v19
	v_mul_f32_e32 v24, v187, v24
	v_mul_f32_e32 v25, v188, v25
	v_mul_f32_e32 v26, v189, v26
	v_fma_f32 v6, v218, v8, v6
	v_fma_f32 v7, v218, v19, v7
	v_fma_f32 v6, v219, v9, v6
	v_fma_f32 v7, v219, v24, v7
	v_fma_f32 v6, v220, v10, v6
	v_fma_f32 v7, v220, v25, v7
	v_fma_f32 v6, v221, v18, v6
	v_fma_f32 v7, v221, v26, v7
	v_mul_f32_e32 v8, 0xbfb8aa3b, v158
	v_mul_f32_e32 v9, 0xbfb8aa3b, v159
	v_mul_f32_e32 v10, 0xbfb8aa3b, v160
	v_mul_f32_e32 v18, 0xbfb8aa3b, v161
	v_mul_f32_e32 v19, 0xbfb8aa3b, v190
	v_mul_f32_e32 v24, 0xbfb8aa3b, v191
	v_mul_f32_e32 v25, 0xbfb8aa3b, v192
	v_mul_f32_e32 v26, 0xbfb8aa3b, v193
	v_exp_f32_e32 v8, v8
	v_exp_f32_e32 v9, v9
	v_exp_f32_e32 v10, v10
	v_exp_f32_e32 v18, v18
	v_exp_f32_e32 v19, v19
	v_exp_f32_e32 v24, v24
	v_exp_f32_e32 v25, v25
	v_exp_f32_e32 v26, v26
	v_add_f32_e32 v8, 1.0, v8
	v_add_f32_e32 v9, 1.0, v9
	v_add_f32_e32 v10, 1.0, v10
	v_add_f32_e32 v18, 1.0, v18
	v_add_f32_e32 v19, 1.0, v19
	v_add_f32_e32 v24, 1.0, v24
	v_add_f32_e32 v25, 1.0, v25
	v_add_f32_e32 v26, 1.0, v26
	v_rcp_f32_e32 v8, v8
	v_rcp_f32_e32 v9, v9
	v_rcp_f32_e32 v10, v10
	v_rcp_f32_e32 v18, v18
	v_rcp_f32_e32 v19, v19
	v_rcp_f32_e32 v24, v24
	v_rcp_f32_e32 v25, v25
	v_rcp_f32_e32 v26, v26
	v_mul_f32_e32 v8, v158, v8
	v_mul_f32_e32 v9, v159, v9
	v_mul_f32_e32 v10, v160, v10
	v_mul_f32_e32 v18, v161, v18
	v_mul_f32_e32 v19, v190, v19
	v_mul_f32_e32 v24, v191, v24
	v_mul_f32_e32 v25, v192, v25
	v_mul_f32_e32 v26, v193, v26
	v_fma_f32 v6, v222, v8, v6
	v_fma_f32 v7, v222, v19, v7
	v_fma_f32 v6, v223, v9, v6
	v_fma_f32 v7, v223, v24, v7
	v_fma_f32 v6, v224, v10, v6
	v_fma_f32 v7, v224, v25, v7
	v_fma_f32 v6, v225, v18, v6
	v_fma_f32 v7, v225, v26, v7
	v_mul_f32_e32 v8, 0xbfb8aa3b, v162
	v_mul_f32_e32 v9, 0xbfb8aa3b, v163
	v_mul_f32_e32 v10, 0xbfb8aa3b, v164
	v_mul_f32_e32 v18, 0xbfb8aa3b, v165
	v_mul_f32_e32 v19, 0xbfb8aa3b, v194
	v_mul_f32_e32 v24, 0xbfb8aa3b, v195
	v_mul_f32_e32 v25, 0xbfb8aa3b, v196
	v_mul_f32_e32 v26, 0xbfb8aa3b, v197
	v_exp_f32_e32 v8, v8
	v_exp_f32_e32 v9, v9
	v_exp_f32_e32 v10, v10
	v_exp_f32_e32 v18, v18
	v_exp_f32_e32 v19, v19
	v_exp_f32_e32 v24, v24
	v_exp_f32_e32 v25, v25
	v_exp_f32_e32 v26, v26
	v_add_f32_e32 v8, 1.0, v8
	v_add_f32_e32 v9, 1.0, v9
	v_add_f32_e32 v10, 1.0, v10
	v_add_f32_e32 v18, 1.0, v18
	v_add_f32_e32 v19, 1.0, v19
	v_add_f32_e32 v24, 1.0, v24
	v_add_f32_e32 v25, 1.0, v25
	v_add_f32_e32 v26, 1.0, v26
	v_rcp_f32_e32 v8, v8
	v_rcp_f32_e32 v9, v9
	v_rcp_f32_e32 v10, v10
	v_rcp_f32_e32 v18, v18
	v_rcp_f32_e32 v19, v19
	v_rcp_f32_e32 v24, v24
	v_rcp_f32_e32 v25, v25
	v_rcp_f32_e32 v26, v26
	v_mul_f32_e32 v8, v162, v8
	v_mul_f32_e32 v9, v163, v9
	v_mul_f32_e32 v10, v164, v10
	v_mul_f32_e32 v18, v165, v18
	v_mul_f32_e32 v19, v194, v19
	v_mul_f32_e32 v24, v195, v24
	v_mul_f32_e32 v25, v196, v25
	v_mul_f32_e32 v26, v197, v26
	v_fma_f32 v6, v226, v8, v6
	v_fma_f32 v7, v226, v19, v7
	v_fma_f32 v6, v227, v9, v6
	v_fma_f32 v7, v227, v24, v7
	v_fma_f32 v6, v228, v10, v6
	v_fma_f32 v7, v228, v25, v7
	v_fma_f32 v6, v229, v18, v6
	v_fma_f32 v7, v229, v26, v7
	v_mul_f32_e32 v8, 0xbfb8aa3b, v166
	v_mul_f32_e32 v9, 0xbfb8aa3b, v167
	v_mul_f32_e32 v10, 0xbfb8aa3b, v168
	v_mul_f32_e32 v18, 0xbfb8aa3b, v169
	v_mul_f32_e32 v19, 0xbfb8aa3b, v198
	v_mul_f32_e32 v24, 0xbfb8aa3b, v199
	v_mul_f32_e32 v25, 0xbfb8aa3b, v200
	v_mul_f32_e32 v26, 0xbfb8aa3b, v201
	v_exp_f32_e32 v8, v8
	v_exp_f32_e32 v9, v9
	v_exp_f32_e32 v10, v10
	v_exp_f32_e32 v18, v18
	v_exp_f32_e32 v19, v19
	v_exp_f32_e32 v24, v24
	v_exp_f32_e32 v25, v25
	v_exp_f32_e32 v26, v26
	v_add_f32_e32 v8, 1.0, v8
	v_add_f32_e32 v9, 1.0, v9
	v_add_f32_e32 v10, 1.0, v10
	v_add_f32_e32 v18, 1.0, v18
	v_add_f32_e32 v19, 1.0, v19
	v_add_f32_e32 v24, 1.0, v24
	v_add_f32_e32 v25, 1.0, v25
	v_add_f32_e32 v26, 1.0, v26
	v_rcp_f32_e32 v8, v8
	v_rcp_f32_e32 v9, v9
	v_rcp_f32_e32 v10, v10
	v_rcp_f32_e32 v18, v18
	v_rcp_f32_e32 v19, v19
	v_rcp_f32_e32 v24, v24
	v_rcp_f32_e32 v25, v25
	v_rcp_f32_e32 v26, v26
	v_mul_f32_e32 v8, v166, v8
	v_mul_f32_e32 v9, v167, v9
	v_mul_f32_e32 v10, v168, v10
	v_mul_f32_e32 v18, v169, v18
	v_mul_f32_e32 v19, v198, v19
	v_mul_f32_e32 v24, v199, v24
	v_mul_f32_e32 v25, v200, v25
	v_mul_f32_e32 v26, v201, v26
	v_fma_f32 v6, v230, v8, v6
	v_fma_f32 v7, v230, v19, v7
	v_fma_f32 v6, v231, v9, v6
	v_fma_f32 v7, v231, v24, v7
	v_fma_f32 v6, v232, v10, v6
	v_fma_f32 v7, v232, v25, v7
	v_fma_f32 v6, v233, v18, v6
	v_fma_f32 v7, v233, v26, v7
	v_mul_f32_e32 v8, 0xbfb8aa3b, v170
	v_mul_f32_e32 v9, 0xbfb8aa3b, v171
	v_mul_f32_e32 v10, 0xbfb8aa3b, v172
	v_mul_f32_e32 v18, 0xbfb8aa3b, v173
	v_mul_f32_e32 v19, 0xbfb8aa3b, v202
	v_mul_f32_e32 v24, 0xbfb8aa3b, v203
	v_mul_f32_e32 v25, 0xbfb8aa3b, v204
	v_mul_f32_e32 v26, 0xbfb8aa3b, v205
	v_exp_f32_e32 v8, v8
	v_exp_f32_e32 v9, v9
	v_exp_f32_e32 v10, v10
	v_exp_f32_e32 v18, v18
	v_exp_f32_e32 v19, v19
	v_exp_f32_e32 v24, v24
	v_exp_f32_e32 v25, v25
	v_exp_f32_e32 v26, v26
	v_add_f32_e32 v8, 1.0, v8
	v_add_f32_e32 v9, 1.0, v9
	v_add_f32_e32 v10, 1.0, v10
	v_add_f32_e32 v18, 1.0, v18
	v_add_f32_e32 v19, 1.0, v19
	v_add_f32_e32 v24, 1.0, v24
	v_add_f32_e32 v25, 1.0, v25
	v_add_f32_e32 v26, 1.0, v26
	v_rcp_f32_e32 v8, v8
	v_rcp_f32_e32 v9, v9
	v_rcp_f32_e32 v10, v10
	v_rcp_f32_e32 v18, v18
	v_rcp_f32_e32 v19, v19
	v_rcp_f32_e32 v24, v24
	v_rcp_f32_e32 v25, v25
	v_rcp_f32_e32 v26, v26
	v_mul_f32_e32 v8, v170, v8
	v_mul_f32_e32 v9, v171, v9
	v_mul_f32_e32 v10, v172, v10
	v_mul_f32_e32 v18, v173, v18
	v_mul_f32_e32 v19, v202, v19
	v_mul_f32_e32 v24, v203, v24
	v_mul_f32_e32 v25, v204, v25
	v_mul_f32_e32 v26, v205, v26
	v_fma_f32 v6, v234, v8, v6
	v_fma_f32 v7, v234, v19, v7
	v_fma_f32 v6, v235, v9, v6
	v_fma_f32 v7, v235, v24, v7
	v_fma_f32 v6, v236, v10, v6
	v_fma_f32 v7, v236, v25, v7
	v_fma_f32 v6, v238, v18, v6
	v_fma_f32 v7, v238, v26, v7
	v_mul_f32_e32 v8, 0xbfb8aa3b, v174
	v_mul_f32_e32 v9, 0xbfb8aa3b, v175
	v_mul_f32_e32 v10, 0xbfb8aa3b, v176
	v_mul_f32_e32 v18, 0xbfb8aa3b, v177
	v_mul_f32_e32 v19, 0xbfb8aa3b, v206
	v_mul_f32_e32 v24, 0xbfb8aa3b, v207
	v_mul_f32_e32 v25, 0xbfb8aa3b, v208
	v_mul_f32_e32 v26, 0xbfb8aa3b, v209
	v_exp_f32_e32 v8, v8
	v_exp_f32_e32 v9, v9
	v_exp_f32_e32 v10, v10
	v_exp_f32_e32 v18, v18
	v_exp_f32_e32 v19, v19
	v_exp_f32_e32 v24, v24
	v_exp_f32_e32 v25, v25
	v_exp_f32_e32 v26, v26
	v_add_f32_e32 v8, 1.0, v8
	v_add_f32_e32 v9, 1.0, v9
	v_add_f32_e32 v10, 1.0, v10
	v_add_f32_e32 v18, 1.0, v18
	v_add_f32_e32 v19, 1.0, v19
	v_add_f32_e32 v24, 1.0, v24
	v_add_f32_e32 v25, 1.0, v25
	v_add_f32_e32 v26, 1.0, v26
	v_rcp_f32_e32 v8, v8
	v_rcp_f32_e32 v9, v9
	v_rcp_f32_e32 v10, v10
	v_rcp_f32_e32 v18, v18
	v_rcp_f32_e32 v19, v19
	v_rcp_f32_e32 v24, v24
	v_rcp_f32_e32 v25, v25
	v_rcp_f32_e32 v26, v26
	v_mul_f32_e32 v8, v174, v8
	v_mul_f32_e32 v9, v175, v9
	v_mul_f32_e32 v10, v176, v10
	v_mul_f32_e32 v18, v177, v18
	v_mul_f32_e32 v19, v206, v19
	v_mul_f32_e32 v24, v207, v24
	v_mul_f32_e32 v25, v208, v25
	v_mul_f32_e32 v26, v209, v26
	v_fma_f32 v6, v239, v8, v6
	v_fma_f32 v7, v239, v19, v7
	v_fma_f32 v6, v240, v9, v6
	v_fma_f32 v7, v240, v24, v7
	v_fma_f32 v6, v241, v10, v6
	v_fma_f32 v7, v241, v25, v7
	v_fma_f32 v6, v242, v18, v6
	v_fma_f32 v7, v242, v26, v7
	ds_write_b64 v23, v[6:7]
	s_waitcnt lgkmcnt(0)
	s_barrier
	s_and_saveexec_b64 s[0:1], s[2:3]
	s_cbranch_execz .LBB0_26
	s_and_b64 s[22:23], s[74:75], exec
	s_cselect_b32 s21, s45, s65
	s_cselect_b32 s22, s44, s64
	v_mov_b32_e32 v4, s22
	v_mov_b32_e32 v5, s21
	v_lshl_add_u64 v[4:5], v[2:3], 2, v[4:5]
	global_load_dword v10, v[4:5], off
	ds_read2st64_b32 v[4:5], v22 offset1:1
	ds_read2st64_b32 v[6:7], v22 offset0:2 offset1:3
	ds_read2st64_b32 v[8:9], v22 offset0:4 offset1:5
	ds_read2st64_b32 v[18:19], v22 offset0:6 offset1:7
	ds_read2st64_b32 v[24:25], v22 offset0:8 offset1:9
	ds_read2st64_b32 v[26:27], v22 offset0:10 offset1:11
	ds_read2st64_b32 v[28:29], v22 offset0:12 offset1:13
	ds_read2st64_b32 v[30:31], v22 offset0:14 offset1:15
	s_waitcnt lgkmcnt(7)
	v_add_f32_e32 v4, 0, v4
	v_add_f32_e32 v4, v4, v5
	s_waitcnt lgkmcnt(6)
	v_add_f32_e32 v4, v4, v6
	v_add_f32_e32 v4, v4, v7
	s_waitcnt lgkmcnt(5)
	v_add_f32_e32 v4, v4, v8
	v_add_f32_e32 v4, v4, v9
	s_waitcnt lgkmcnt(4)
	v_add_f32_e32 v4, v4, v18
	v_add_f32_e32 v4, v4, v19
	s_waitcnt lgkmcnt(3)
	v_add_f32_e32 v4, v4, v24
	v_add_f32_e32 v4, v4, v25
	s_waitcnt lgkmcnt(2)
	v_add_f32_e32 v4, v4, v26
	v_add_f32_e32 v4, v4, v27
	s_waitcnt lgkmcnt(1)
	v_add_f32_e32 v4, v4, v28
	v_lshl_add_u32 v3, s6, 1, v21
	v_add_f32_e32 v4, v4, v29
	v_mad_u64_u32 v[2:3], s[22:23], v3, s19, v[2:3]
	s_waitcnt lgkmcnt(0)
	v_add_f32_e32 v4, v4, v30
	v_ashrrev_i32_e32 v3, 31, v2
	v_add_f32_e32 v4, v4, v31
	v_lshl_add_u64 v[2:3], v[2:3], 2, s[28:29]
	s_waitcnt vmcnt(0)
	v_add_f32_e32 v4, v4, v10
	global_store_dword v[2:3], v4, off
	s_branch .LBB0_26

.LBB0_82:
	s_or_b64 exec, exec, s[0:1]
	v_mov_b32 v0, v144
	s_lshl_b32 s0, s94, 3
	v_ashrrev_i32_e32 v1, 6, v0
	v_writelane_b32 v237, s0, 19
	v_add_u32_e32 v16, s0, v1
	s_movk_i32 s0, 0x4000
	v_cmp_gt_i32_e32 vcc, s0, v16
	s_and_saveexec_b64 s[2:3], vcc
	s_cbranch_execz .LBB0_89
	v_and_b32_e32 v1, 63, v0
	v_lshlrev_b32_e32 v2, 4, v1
	v_readfirstlane_b32 s0, v16
	s_nop 3
	v_lshrrev_b32_e32 v7, 4, v1
	v_and_b32_e32 v8, 15, v1
	v_lshlrev_b32_e32 v8, 3, v8
	v_add_u32_e32 v9, 0, v7
	v_lshl_add_u32 v3, v9, 21, v8
	v_add_u32_e32 v9, 4, v7
	v_lshl_add_u32 v4, v9, 21, v8
	v_add_u32_e32 v9, 8, v7
	v_lshl_add_u32 v5, v9, 21, v8
	v_add_u32_e32 v9, 12, v7
	v_lshl_add_u32 v6, v9, 21, v8
	v_mov_b32_e32 v11, 0x358637bd
	s_lshl_b32 s1, s0, 12
	s_add_u32 s4, s36, s1
	s_addc_u32 s5, s37, 0
	s_lshl_b32 s1, s0, 7
	s_add_u32 s10, s28, 0x1c00000
	s_addc_u32 s11, s29, 0
	s_add_u32 s10, s10, s1
	s_addc_u32 s11, s11, 0
	global_load_dwordx4 v[146:149], v2, s[46:47] offset:0
	global_load_dwordx4 v[150:153], v2, s[46:47] offset:1024
	global_load_dwordx4 v[154:157], v2, s[46:47] offset:2048
	global_load_dwordx4 v[158:161], v2, s[46:47] offset:3072
	s_add_u32 s6, s28, 0x1000
	s_addc_u32 s7, s29, 0
	s_add_u32 s8, s28, 0x0
	s_addc_u32 s9, s29, 0
	global_load_dwordx4 v[162:165], v2, s[6:7] offset:0
	global_load_dwordx4 v[166:169], v2, s[6:7] offset:1024
	global_load_dwordx4 v[170:173], v2, s[6:7] offset:2048
	global_load_dwordx4 v[174:177], v2, s[6:7] offset:3072
	global_load_dwordx4 v[178:181], v2, s[8:9] offset:0
	global_load_dwordx4 v[182:185], v2, s[8:9] offset:1024
	global_load_dwordx4 v[186:189], v2, s[8:9] offset:2048
	global_load_dwordx4 v[190:193], v2, s[8:9] offset:3072
	s_add_u32 s6, s28, 0x4000
	s_addc_u32 s7, s29, 0
	s_add_u32 s8, s28, 0x3000
	s_addc_u32 s9, s29, 0
	global_load_dwordx4 v[194:197], v2, s[6:7] offset:0
	global_load_dwordx4 v[198:201], v2, s[6:7] offset:1024
	global_load_dwordx4 v[202:205], v2, s[6:7] offset:2048
	global_load_dwordx4 v[206:209], v2, s[6:7] offset:3072
	global_load_dwordx4 v[210:213], v2, s[8:9] offset:0
	global_load_dwordx4 v[214:217], v2, s[8:9] offset:1024
	global_load_dwordx4 v[218:221], v2, s[8:9] offset:2048
	global_load_dwordx4 v[222:225], v2, s[8:9] offset:3072
	global_load_dwordx4 v[16:19], v2, s[4:5] offset:0
	global_load_dwordx4 v[20:23], v2, s[4:5] offset:1024
	global_load_dwordx4 v[24:27], v2, s[4:5] offset:2048
	global_load_dwordx4 v[28:31], v2, s[4:5] offset:3072
	s_add_u32 s4, s4, 0x800000
	s_addc_u32 s5, s5, 0
	global_load_dwordx4 v[32:35], v2, s[4:5] offset:0
	global_load_dwordx4 v[36:39], v2, s[4:5] offset:1024
	global_load_dwordx4 v[40:43], v2, s[4:5] offset:2048
	global_load_dwordx4 v[44:47], v2, s[4:5] offset:3072
	s_add_u32 s4, s4, 0x800000
	s_addc_u32 s5, s5, 0
	global_load_dwordx4 v[48:51], v2, s[4:5] offset:0
	global_load_dwordx4 v[52:55], v2, s[4:5] offset:1024
	global_load_dwordx4 v[56:59], v2, s[4:5] offset:2048
	global_load_dwordx4 v[60:63], v2, s[4:5] offset:3072
	s_add_u32 s4, s4, 0x800000
	s_addc_u32 s5, s5, 0
	global_load_dwordx4 v[64:67], v2, s[4:5] offset:0
	global_load_dwordx4 v[68:71], v2, s[4:5] offset:1024
	global_load_dwordx4 v[72:75], v2, s[4:5] offset:2048
	global_load_dwordx4 v[76:79], v2, s[4:5] offset:3072
	s_add_u32 s4, s4, 0x800000
	s_addc_u32 s5, s5, 0
	global_load_dwordx4 v[80:83], v2, s[4:5] offset:0
	global_load_dwordx4 v[84:87], v2, s[4:5] offset:1024
	global_load_dwordx4 v[88:91], v2, s[4:5] offset:2048
	global_load_dwordx4 v[92:95], v2, s[4:5] offset:3072
	s_add_u32 s4, s4, 0x800000
	s_addc_u32 s5, s5, 0
	global_load_dwordx4 v[96:99], v2, s[4:5] offset:0
	global_load_dwordx4 v[100:103], v2, s[4:5] offset:1024
	global_load_dwordx4 v[104:107], v2, s[4:5] offset:2048
	global_load_dwordx4 v[108:111], v2, s[4:5] offset:3072
	s_add_u32 s4, s4, 0x800000
	s_addc_u32 s5, s5, 0
	global_load_dwordx4 v[112:115], v2, s[4:5] offset:0
	global_load_dwordx4 v[116:119], v2, s[4:5] offset:1024
	global_load_dwordx4 v[120:123], v2, s[4:5] offset:2048
	global_load_dwordx4 v[124:127], v2, s[4:5] offset:3072
	s_add_u32 s4, s4, 0x800000
	s_addc_u32 s5, s5, 0
	global_load_dwordx4 v[128:131], v2, s[4:5] offset:0
	global_load_dwordx4 v[132:135], v2, s[4:5] offset:1024
	global_load_dwordx4 v[136:139], v2, s[4:5] offset:2048
	global_load_dwordx4 v[140:143], v2, s[4:5] offset:3072
	s_waitcnt vmcnt(32)
	v_add_f32_e32 v162, 1.0, v162
	v_add_f32_e32 v163, 1.0, v163
	v_add_f32_e32 v164, 1.0, v164
	v_add_f32_e32 v165, 1.0, v165
	v_add_f32_e32 v166, 1.0, v166
	v_add_f32_e32 v167, 1.0, v167
	v_add_f32_e32 v168, 1.0, v168
	v_add_f32_e32 v169, 1.0, v169
	v_add_f32_e32 v170, 1.0, v170
	v_add_f32_e32 v171, 1.0, v171
	v_add_f32_e32 v172, 1.0, v172
	v_add_f32_e32 v173, 1.0, v173
	v_add_f32_e32 v174, 1.0, v174
	v_add_f32_e32 v175, 1.0, v175
	v_add_f32_e32 v176, 1.0, v176
	v_add_f32_e32 v177, 1.0, v177
	v_add_f32_e32 v194, 1.0, v194
	v_add_f32_e32 v195, 1.0, v195
	v_add_f32_e32 v196, 1.0, v196
	v_add_f32_e32 v197, 1.0, v197
	v_add_f32_e32 v198, 1.0, v198
	v_add_f32_e32 v199, 1.0, v199
	v_add_f32_e32 v200, 1.0, v200
	v_add_f32_e32 v201, 1.0, v201
	v_add_f32_e32 v202, 1.0, v202
	v_add_f32_e32 v203, 1.0, v203
	v_add_f32_e32 v204, 1.0, v204
	v_add_f32_e32 v205, 1.0, v205
	v_add_f32_e32 v206, 1.0, v206
	v_add_f32_e32 v207, 1.0, v207
	v_add_f32_e32 v208, 1.0, v208
	v_add_f32_e32 v209, 1.0, v209
	s_waitcnt vmcnt(28)
	v_mul_f32_e32 v12, v16, v16
	v_mul_f32_e32 v13, v17, v17
	v_fmac_f32_e32 v12, v18, v18
	v_fmac_f32_e32 v13, v19, v19
	v_fmac_f32_e32 v12, v20, v20
	v_fmac_f32_e32 v13, v21, v21
	v_fmac_f32_e32 v12, v22, v22
	v_fmac_f32_e32 v13, v23, v23
	v_fmac_f32_e32 v12, v24, v24
	v_fmac_f32_e32 v13, v25, v25
	v_fmac_f32_e32 v12, v26, v26
	v_fmac_f32_e32 v13, v27, v27
	v_fmac_f32_e32 v12, v28, v28
	v_fmac_f32_e32 v13, v29, v29
	v_fmac_f32_e32 v12, v30, v30
	v_fmac_f32_e32 v13, v31, v31
	v_add_f32_e32 v12, v12, v13
	s_nop 0
	s_nop 0
	v_add_f32_dpp v12, v12, v12 quad_perm:[1,0,3,2] row_mask:0xf bank_mask:0xf
	s_nop 0
	s_nop 0
	v_add_f32_dpp v12, v12, v12 quad_perm:[2,3,0,1] row_mask:0xf bank_mask:0xf
	s_nop 0
	s_nop 0
	v_add_f32_dpp v12, v12, v12 row_half_mirror row_mask:0xf bank_mask:0xf
	s_nop 0
	s_nop 0
	v_add_f32_dpp v12, v12, v12 row_mirror row_mask:0xf bank_mask:0xf
	v_mov_b32_e32 v13, v12
	s_nop 0
	s_nop 0
	v_permlane16_swap_b32_e32 v12, v13
	v_add_f32_e32 v12, v12, v13
	v_mov_b32_e32 v13, v12
	s_nop 0
	s_nop 0
	v_permlane32_swap_b32_e32 v12, v13
	v_add_f32_e32 v12, v12, v13
	v_fmamk_f32 v12, v12, 0x3a800000, v11
	v_rsq_f32_e32 v10, v12
	s_nop 0
	v_mul_f32_e32 v16, v16, v10
	v_mul_f32_e32 v17, v17, v10
	v_mul_f32_e32 v18, v18, v10
	v_mul_f32_e32 v19, v19, v10
	v_mul_f32_e32 v20, v20, v10
	v_mul_f32_e32 v21, v21, v10
	v_mul_f32_e32 v22, v22, v10
	v_mul_f32_e32 v23, v23, v10
	v_mul_f32_e32 v24, v24, v10
	v_mul_f32_e32 v25, v25, v10
	v_mul_f32_e32 v26, v26, v10
	v_mul_f32_e32 v27, v27, v10
	v_mul_f32_e32 v28, v28, v10
	v_mul_f32_e32 v29, v29, v10
	v_mul_f32_e32 v30, v30, v10
	v_mul_f32_e32 v31, v31, v10
	v_mul_f32_e32 v16, v16, v146
	v_mul_f32_e32 v17, v17, v147
	v_mul_f32_e32 v18, v18, v148
	v_mul_f32_e32 v19, v19, v149
	v_mul_f32_e32 v20, v20, v150
	v_mul_f32_e32 v21, v21, v151
	v_mul_f32_e32 v22, v22, v152
	v_mul_f32_e32 v23, v23, v153
	v_mul_f32_e32 v24, v24, v154
	v_mul_f32_e32 v25, v25, v155
	v_mul_f32_e32 v26, v26, v156
	v_mul_f32_e32 v27, v27, v157
	v_mul_f32_e32 v28, v28, v158
	v_mul_f32_e32 v29, v29, v159
	v_mul_f32_e32 v30, v30, v160
	v_mul_f32_e32 v31, v31, v161
	v_fma_f32 v16, v16, v162, v178
	v_fma_f32 v17, v17, v163, v179
	v_fma_f32 v18, v18, v164, v180
	v_fma_f32 v19, v19, v165, v181
	v_fma_f32 v20, v20, v166, v182
	v_fma_f32 v21, v21, v167, v183
	v_fma_f32 v22, v22, v168, v184
	v_fma_f32 v23, v23, v169, v185
	v_fma_f32 v24, v24, v170, v186
	v_fma_f32 v25, v25, v171, v187
	v_fma_f32 v26, v26, v172, v188
	v_fma_f32 v27, v27, v173, v189
	v_fma_f32 v28, v28, v174, v190
	v_fma_f32 v29, v29, v175, v191
	v_fma_f32 v30, v30, v176, v192
	v_fma_f32 v31, v31, v177, v193
	v_cvt_pk_bf16_f32 v226, v16, v17
	v_cvt_pk_bf16_f32 v227, v18, v19
	v_cvt_pk_bf16_f32 v228, v20, v21
	v_cvt_pk_bf16_f32 v229, v22, v23
	v_cvt_pk_bf16_f32 v230, v24, v25
	v_cvt_pk_bf16_f32 v231, v26, v27
	v_cvt_pk_bf16_f32 v232, v28, v29
	v_cvt_pk_bf16_f32 v233, v30, v31
	global_store_dwordx2 v3, v[226:227], s[10:11]
	global_store_dwordx2 v4, v[228:229], s[10:11]
	global_store_dwordx2 v5, v[230:231], s[10:11]
	global_store_dwordx2 v6, v[232:233], s[10:11]
	s_add_u32 s10, s10, 0x40000
	s_addc_u32 s11, s11, 0
	s_nop 0
	s_waitcnt vmcnt(28)
	v_mul_f32_e32 v12, v32, v32
	v_mul_f32_e32 v13, v33, v33
	v_fmac_f32_e32 v12, v34, v34
	v_fmac_f32_e32 v13, v35, v35
	v_fmac_f32_e32 v12, v36, v36
	v_fmac_f32_e32 v13, v37, v37
	v_fmac_f32_e32 v12, v38, v38
	v_fmac_f32_e32 v13, v39, v39
	v_fmac_f32_e32 v12, v40, v40
	v_fmac_f32_e32 v13, v41, v41
	v_fmac_f32_e32 v12, v42, v42
	v_fmac_f32_e32 v13, v43, v43
	v_fmac_f32_e32 v12, v44, v44
	v_fmac_f32_e32 v13, v45, v45
	v_fmac_f32_e32 v12, v46, v46
	v_fmac_f32_e32 v13, v47, v47
	v_add_f32_e32 v12, v12, v13
	s_nop 0
	s_nop 0
	v_add_f32_dpp v12, v12, v12 quad_perm:[1,0,3,2] row_mask:0xf bank_mask:0xf
	s_nop 0
	s_nop 0
	v_add_f32_dpp v12, v12, v12 quad_perm:[2,3,0,1] row_mask:0xf bank_mask:0xf
	s_nop 0
	s_nop 0
	v_add_f32_dpp v12, v12, v12 row_half_mirror row_mask:0xf bank_mask:0xf
	s_nop 0
	s_nop 0
	v_add_f32_dpp v12, v12, v12 row_mirror row_mask:0xf bank_mask:0xf
	v_mov_b32_e32 v13, v12
	s_nop 0
	s_nop 0
	v_permlane16_swap_b32_e32 v12, v13
	v_add_f32_e32 v12, v12, v13
	v_mov_b32_e32 v13, v12
	s_nop 0
	s_nop 0
	v_permlane32_swap_b32_e32 v12, v13
	v_add_f32_e32 v12, v12, v13
	v_fmamk_f32 v12, v12, 0x3a800000, v11
	v_rsq_f32_e32 v10, v12
	s_nop 0
	v_mul_f32_e32 v32, v32, v10
	v_mul_f32_e32 v33, v33, v10
	v_mul_f32_e32 v34, v34, v10
	v_mul_f32_e32 v35, v35, v10
	v_mul_f32_e32 v36, v36, v10
	v_mul_f32_e32 v37, v37, v10
	v_mul_f32_e32 v38, v38, v10
	v_mul_f32_e32 v39, v39, v10
	v_mul_f32_e32 v40, v40, v10
	v_mul_f32_e32 v41, v41, v10
	v_mul_f32_e32 v42, v42, v10
	v_mul_f32_e32 v43, v43, v10
	v_mul_f32_e32 v44, v44, v10
	v_mul_f32_e32 v45, v45, v10
	v_mul_f32_e32 v46, v46, v10
	v_mul_f32_e32 v47, v47, v10
	v_mul_f32_e32 v32, v32, v146
	v_mul_f32_e32 v33, v33, v147
	v_mul_f32_e32 v34, v34, v148
	v_mul_f32_e32 v35, v35, v149
	v_mul_f32_e32 v36, v36, v150
	v_mul_f32_e32 v37, v37, v151
	v_mul_f32_e32 v38, v38, v152
	v_mul_f32_e32 v39, v39, v153
	v_mul_f32_e32 v40, v40, v154
	v_mul_f32_e32 v41, v41, v155
	v_mul_f32_e32 v42, v42, v156
	v_mul_f32_e32 v43, v43, v157
	v_mul_f32_e32 v44, v44, v158
	v_mul_f32_e32 v45, v45, v159
	v_mul_f32_e32 v46, v46, v160
	v_mul_f32_e32 v47, v47, v161
	v_fma_f32 v32, v32, v162, v178
	v_fma_f32 v33, v33, v163, v179
	v_fma_f32 v34, v34, v164, v180
	v_fma_f32 v35, v35, v165, v181
	v_fma_f32 v36, v36, v166, v182
	v_fma_f32 v37, v37, v167, v183
	v_fma_f32 v38, v38, v168, v184
	v_fma_f32 v39, v39, v169, v185
	v_fma_f32 v40, v40, v170, v186
	v_fma_f32 v41, v41, v171, v187
	v_fma_f32 v42, v42, v172, v188
	v_fma_f32 v43, v43, v173, v189
	v_fma_f32 v44, v44, v174, v190
	v_fma_f32 v45, v45, v175, v191
	v_fma_f32 v46, v46, v176, v192
	v_fma_f32 v47, v47, v177, v193
	v_cvt_pk_bf16_f32 v226, v32, v33
	v_cvt_pk_bf16_f32 v227, v34, v35
	v_cvt_pk_bf16_f32 v228, v36, v37
	v_cvt_pk_bf16_f32 v229, v38, v39
	v_cvt_pk_bf16_f32 v230, v40, v41
	v_cvt_pk_bf16_f32 v231, v42, v43
	v_cvt_pk_bf16_f32 v232, v44, v45
	v_cvt_pk_bf16_f32 v233, v46, v47
	global_store_dwordx2 v3, v[226:227], s[10:11]
	global_store_dwordx2 v4, v[228:229], s[10:11]
	global_store_dwordx2 v5, v[230:231], s[10:11]
	global_store_dwordx2 v6, v[232:233], s[10:11]
	s_add_u32 s10, s10, 0x40000
	s_addc_u32 s11, s11, 0
	s_nop 0
	s_waitcnt vmcnt(28)
	v_mul_f32_e32 v12, v48, v48
	v_mul_f32_e32 v13, v49, v49
	v_fmac_f32_e32 v12, v50, v50
	v_fmac_f32_e32 v13, v51, v51
	v_fmac_f32_e32 v12, v52, v52
	v_fmac_f32_e32 v13, v53, v53
	v_fmac_f32_e32 v12, v54, v54
	v_fmac_f32_e32 v13, v55, v55
	v_fmac_f32_e32 v12, v56, v56
	v_fmac_f32_e32 v13, v57, v57
	v_fmac_f32_e32 v12, v58, v58
	v_fmac_f32_e32 v13, v59, v59
	v_fmac_f32_e32 v12, v60, v60
	v_fmac_f32_e32 v13, v61, v61
	v_fmac_f32_e32 v12, v62, v62
	v_fmac_f32_e32 v13, v63, v63
	v_add_f32_e32 v12, v12, v13
	s_nop 0
	s_nop 0
	v_add_f32_dpp v12, v12, v12 quad_perm:[1,0,3,2] row_mask:0xf bank_mask:0xf
	s_nop 0
	s_nop 0
	v_add_f32_dpp v12, v12, v12 quad_perm:[2,3,0,1] row_mask:0xf bank_mask:0xf
	s_nop 0
	s_nop 0
	v_add_f32_dpp v12, v12, v12 row_half_mirror row_mask:0xf bank_mask:0xf
	s_nop 0
	s_nop 0
	v_add_f32_dpp v12, v12, v12 row_mirror row_mask:0xf bank_mask:0xf
	v_mov_b32_e32 v13, v12
	s_nop 0
	s_nop 0
	v_permlane16_swap_b32_e32 v12, v13
	v_add_f32_e32 v12, v12, v13
	v_mov_b32_e32 v13, v12
	s_nop 0
	s_nop 0
	v_permlane32_swap_b32_e32 v12, v13
	v_add_f32_e32 v12, v12, v13
	v_fmamk_f32 v12, v12, 0x3a800000, v11
	v_rsq_f32_e32 v10, v12
	s_nop 0
	v_mul_f32_e32 v48, v48, v10
	v_mul_f32_e32 v49, v49, v10
	v_mul_f32_e32 v50, v50, v10
	v_mul_f32_e32 v51, v51, v10
	v_mul_f32_e32 v52, v52, v10
	v_mul_f32_e32 v53, v53, v10
	v_mul_f32_e32 v54, v54, v10
	v_mul_f32_e32 v55, v55, v10
	v_mul_f32_e32 v56, v56, v10
	v_mul_f32_e32 v57, v57, v10
	v_mul_f32_e32 v58, v58, v10
	v_mul_f32_e32 v59, v59, v10
	v_mul_f32_e32 v60, v60, v10
	v_mul_f32_e32 v61, v61, v10
	v_mul_f32_e32 v62, v62, v10
	v_mul_f32_e32 v63, v63, v10
	v_mul_f32_e32 v48, v48, v146
	v_mul_f32_e32 v49, v49, v147
	v_mul_f32_e32 v50, v50, v148
	v_mul_f32_e32 v51, v51, v149
	v_mul_f32_e32 v52, v52, v150
	v_mul_f32_e32 v53, v53, v151
	v_mul_f32_e32 v54, v54, v152
	v_mul_f32_e32 v55, v55, v153
	v_mul_f32_e32 v56, v56, v154
	v_mul_f32_e32 v57, v57, v155
	v_mul_f32_e32 v58, v58, v156
	v_mul_f32_e32 v59, v59, v157
	v_mul_f32_e32 v60, v60, v158
	v_mul_f32_e32 v61, v61, v159
	v_mul_f32_e32 v62, v62, v160
	v_mul_f32_e32 v63, v63, v161
	v_fma_f32 v48, v48, v162, v178
	v_fma_f32 v49, v49, v163, v179
	v_fma_f32 v50, v50, v164, v180
	v_fma_f32 v51, v51, v165, v181
	v_fma_f32 v52, v52, v166, v182
	v_fma_f32 v53, v53, v167, v183
	v_fma_f32 v54, v54, v168, v184
	v_fma_f32 v55, v55, v169, v185
	v_fma_f32 v56, v56, v170, v186
	v_fma_f32 v57, v57, v171, v187
	v_fma_f32 v58, v58, v172, v188
	v_fma_f32 v59, v59, v173, v189
	v_fma_f32 v60, v60, v174, v190
	v_fma_f32 v61, v61, v175, v191
	v_fma_f32 v62, v62, v176, v192
	v_fma_f32 v63, v63, v177, v193
	v_cvt_pk_bf16_f32 v226, v48, v49
	v_cvt_pk_bf16_f32 v227, v50, v51
	v_cvt_pk_bf16_f32 v228, v52, v53
	v_cvt_pk_bf16_f32 v229, v54, v55
	v_cvt_pk_bf16_f32 v230, v56, v57
	v_cvt_pk_bf16_f32 v231, v58, v59
	v_cvt_pk_bf16_f32 v232, v60, v61
	v_cvt_pk_bf16_f32 v233, v62, v63
	global_store_dwordx2 v3, v[226:227], s[10:11]
	global_store_dwordx2 v4, v[228:229], s[10:11]
	global_store_dwordx2 v5, v[230:231], s[10:11]
	global_store_dwordx2 v6, v[232:233], s[10:11]
	s_add_u32 s10, s10, 0x40000
	s_addc_u32 s11, s11, 0
	s_nop 0
	s_waitcnt vmcnt(28)
	v_mul_f32_e32 v12, v64, v64
	v_mul_f32_e32 v13, v65, v65
	v_fmac_f32_e32 v12, v66, v66
	v_fmac_f32_e32 v13, v67, v67
	v_fmac_f32_e32 v12, v68, v68
	v_fmac_f32_e32 v13, v69, v69
	v_fmac_f32_e32 v12, v70, v70
	v_fmac_f32_e32 v13, v71, v71
	v_fmac_f32_e32 v12, v72, v72
	v_fmac_f32_e32 v13, v73, v73
	v_fmac_f32_e32 v12, v74, v74
	v_fmac_f32_e32 v13, v75, v75
	v_fmac_f32_e32 v12, v76, v76
	v_fmac_f32_e32 v13, v77, v77
	v_fmac_f32_e32 v12, v78, v78
	v_fmac_f32_e32 v13, v79, v79
	v_add_f32_e32 v12, v12, v13
	s_nop 0
	s_nop 0
	v_add_f32_dpp v12, v12, v12 quad_perm:[1,0,3,2] row_mask:0xf bank_mask:0xf
	s_nop 0
	s_nop 0
	v_add_f32_dpp v12, v12, v12 quad_perm:[2,3,0,1] row_mask:0xf bank_mask:0xf
	s_nop 0
	s_nop 0
	v_add_f32_dpp v12, v12, v12 row_half_mirror row_mask:0xf bank_mask:0xf
	s_nop 0
	s_nop 0
	v_add_f32_dpp v12, v12, v12 row_mirror row_mask:0xf bank_mask:0xf
	v_mov_b32_e32 v13, v12
	s_nop 0
	s_nop 0
	v_permlane16_swap_b32_e32 v12, v13
	v_add_f32_e32 v12, v12, v13
	v_mov_b32_e32 v13, v12
	s_nop 0
	s_nop 0
	v_permlane32_swap_b32_e32 v12, v13
	v_add_f32_e32 v12, v12, v13
	v_fmamk_f32 v12, v12, 0x3a800000, v11
	v_rsq_f32_e32 v10, v12
	s_nop 0
	v_mul_f32_e32 v64, v64, v10
	v_mul_f32_e32 v65, v65, v10
	v_mul_f32_e32 v66, v66, v10
	v_mul_f32_e32 v67, v67, v10
	v_mul_f32_e32 v68, v68, v10
	v_mul_f32_e32 v69, v69, v10
	v_mul_f32_e32 v70, v70, v10
	v_mul_f32_e32 v71, v71, v10
	v_mul_f32_e32 v72, v72, v10
	v_mul_f32_e32 v73, v73, v10
	v_mul_f32_e32 v74, v74, v10
	v_mul_f32_e32 v75, v75, v10
	v_mul_f32_e32 v76, v76, v10
	v_mul_f32_e32 v77, v77, v10
	v_mul_f32_e32 v78, v78, v10
	v_mul_f32_e32 v79, v79, v10
	v_mul_f32_e32 v64, v64, v146
	v_mul_f32_e32 v65, v65, v147
	v_mul_f32_e32 v66, v66, v148
	v_mul_f32_e32 v67, v67, v149
	v_mul_f32_e32 v68, v68, v150
	v_mul_f32_e32 v69, v69, v151
	v_mul_f32_e32 v70, v70, v152
	v_mul_f32_e32 v71, v71, v153
	v_mul_f32_e32 v72, v72, v154
	v_mul_f32_e32 v73, v73, v155
	v_mul_f32_e32 v74, v74, v156
	v_mul_f32_e32 v75, v75, v157
	v_mul_f32_e32 v76, v76, v158
	v_mul_f32_e32 v77, v77, v159
	v_mul_f32_e32 v78, v78, v160
	v_mul_f32_e32 v79, v79, v161
	v_fma_f32 v64, v64, v162, v178
	v_fma_f32 v65, v65, v163, v179
	v_fma_f32 v66, v66, v164, v180
	v_fma_f32 v67, v67, v165, v181
	v_fma_f32 v68, v68, v166, v182
	v_fma_f32 v69, v69, v167, v183
	v_fma_f32 v70, v70, v168, v184
	v_fma_f32 v71, v71, v169, v185
	v_fma_f32 v72, v72, v170, v186
	v_fma_f32 v73, v73, v171, v187
	v_fma_f32 v74, v74, v172, v188
	v_fma_f32 v75, v75, v173, v189
	v_fma_f32 v76, v76, v174, v190
	v_fma_f32 v77, v77, v175, v191
	v_fma_f32 v78, v78, v176, v192
	v_fma_f32 v79, v79, v177, v193
	v_cvt_pk_bf16_f32 v226, v64, v65
	v_cvt_pk_bf16_f32 v227, v66, v67
	v_cvt_pk_bf16_f32 v228, v68, v69
	v_cvt_pk_bf16_f32 v229, v70, v71
	v_cvt_pk_bf16_f32 v230, v72, v73
	v_cvt_pk_bf16_f32 v231, v74, v75
	v_cvt_pk_bf16_f32 v232, v76, v77
	v_cvt_pk_bf16_f32 v233, v78, v79
	global_store_dwordx2 v3, v[226:227], s[10:11]
	global_store_dwordx2 v4, v[228:229], s[10:11]
	global_store_dwordx2 v5, v[230:231], s[10:11]
	global_store_dwordx2 v6, v[232:233], s[10:11]
	s_add_u32 s10, s10, 0x40000
	s_addc_u32 s11, s11, 0
	s_nop 0
	s_waitcnt vmcnt(28)
	v_mul_f32_e32 v12, v80, v80
	v_mul_f32_e32 v13, v81, v81
	v_fmac_f32_e32 v12, v82, v82
	v_fmac_f32_e32 v13, v83, v83
	v_fmac_f32_e32 v12, v84, v84
	v_fmac_f32_e32 v13, v85, v85
	v_fmac_f32_e32 v12, v86, v86
	v_fmac_f32_e32 v13, v87, v87
	v_fmac_f32_e32 v12, v88, v88
	v_fmac_f32_e32 v13, v89, v89
	v_fmac_f32_e32 v12, v90, v90
	v_fmac_f32_e32 v13, v91, v91
	v_fmac_f32_e32 v12, v92, v92
	v_fmac_f32_e32 v13, v93, v93
	v_fmac_f32_e32 v12, v94, v94
	v_fmac_f32_e32 v13, v95, v95
	v_add_f32_e32 v12, v12, v13
	s_nop 0
	s_nop 0
	v_add_f32_dpp v12, v12, v12 quad_perm:[1,0,3,2] row_mask:0xf bank_mask:0xf
	s_nop 0
	s_nop 0
	v_add_f32_dpp v12, v12, v12 quad_perm:[2,3,0,1] row_mask:0xf bank_mask:0xf
	s_nop 0
	s_nop 0
	v_add_f32_dpp v12, v12, v12 row_half_mirror row_mask:0xf bank_mask:0xf
	s_nop 0
	s_nop 0
	v_add_f32_dpp v12, v12, v12 row_mirror row_mask:0xf bank_mask:0xf
	v_mov_b32_e32 v13, v12
	s_nop 0
	s_nop 0
	v_permlane16_swap_b32_e32 v12, v13
	v_add_f32_e32 v12, v12, v13
	v_mov_b32_e32 v13, v12
	s_nop 0
	s_nop 0
	v_permlane32_swap_b32_e32 v12, v13
	v_add_f32_e32 v12, v12, v13
	v_fmamk_f32 v12, v12, 0x3a800000, v11
	v_rsq_f32_e32 v10, v12
	s_nop 0
	v_mul_f32_e32 v80, v80, v10
	v_mul_f32_e32 v81, v81, v10
	v_mul_f32_e32 v82, v82, v10
	v_mul_f32_e32 v83, v83, v10
	v_mul_f32_e32 v84, v84, v10
	v_mul_f32_e32 v85, v85, v10
	v_mul_f32_e32 v86, v86, v10
	v_mul_f32_e32 v87, v87, v10
	v_mul_f32_e32 v88, v88, v10
	v_mul_f32_e32 v89, v89, v10
	v_mul_f32_e32 v90, v90, v10
	v_mul_f32_e32 v91, v91, v10
	v_mul_f32_e32 v92, v92, v10
	v_mul_f32_e32 v93, v93, v10
	v_mul_f32_e32 v94, v94, v10
	v_mul_f32_e32 v95, v95, v10
	v_mul_f32_e32 v80, v80, v146
	v_mul_f32_e32 v81, v81, v147
	v_mul_f32_e32 v82, v82, v148
	v_mul_f32_e32 v83, v83, v149
	v_mul_f32_e32 v84, v84, v150
	v_mul_f32_e32 v85, v85, v151
	v_mul_f32_e32 v86, v86, v152
	v_mul_f32_e32 v87, v87, v153
	v_mul_f32_e32 v88, v88, v154
	v_mul_f32_e32 v89, v89, v155
	v_mul_f32_e32 v90, v90, v156
	v_mul_f32_e32 v91, v91, v157
	v_mul_f32_e32 v92, v92, v158
	v_mul_f32_e32 v93, v93, v159
	v_mul_f32_e32 v94, v94, v160
	v_mul_f32_e32 v95, v95, v161
	v_fma_f32 v80, v80, v194, v210
	v_fma_f32 v81, v81, v195, v211
	v_fma_f32 v82, v82, v196, v212
	v_fma_f32 v83, v83, v197, v213
	v_fma_f32 v84, v84, v198, v214
	v_fma_f32 v85, v85, v199, v215
	v_fma_f32 v86, v86, v200, v216
	v_fma_f32 v87, v87, v201, v217
	v_fma_f32 v88, v88, v202, v218
	v_fma_f32 v89, v89, v203, v219
	v_fma_f32 v90, v90, v204, v220
	v_fma_f32 v91, v91, v205, v221
	v_fma_f32 v92, v92, v206, v222
	v_fma_f32 v93, v93, v207, v223
	v_fma_f32 v94, v94, v208, v224
	v_fma_f32 v95, v95, v209, v225
	v_cvt_pk_bf16_f32 v226, v80, v81
	v_cvt_pk_bf16_f32 v227, v82, v83
	v_cvt_pk_bf16_f32 v228, v84, v85
	v_cvt_pk_bf16_f32 v229, v86, v87
	v_cvt_pk_bf16_f32 v230, v88, v89
	v_cvt_pk_bf16_f32 v231, v90, v91
	v_cvt_pk_bf16_f32 v232, v92, v93
	v_cvt_pk_bf16_f32 v233, v94, v95
	global_store_dwordx2 v3, v[226:227], s[10:11]
	global_store_dwordx2 v4, v[228:229], s[10:11]
	global_store_dwordx2 v5, v[230:231], s[10:11]
	global_store_dwordx2 v6, v[232:233], s[10:11]
	s_add_u32 s10, s10, 0x40000
	s_addc_u32 s11, s11, 0
	s_nop 0
	s_waitcnt vmcnt(28)
	v_mul_f32_e32 v12, v96, v96
	v_mul_f32_e32 v13, v97, v97
	v_fmac_f32_e32 v12, v98, v98
	v_fmac_f32_e32 v13, v99, v99
	v_fmac_f32_e32 v12, v100, v100
	v_fmac_f32_e32 v13, v101, v101
	v_fmac_f32_e32 v12, v102, v102
	v_fmac_f32_e32 v13, v103, v103
	v_fmac_f32_e32 v12, v104, v104
	v_fmac_f32_e32 v13, v105, v105
	v_fmac_f32_e32 v12, v106, v106
	v_fmac_f32_e32 v13, v107, v107
	v_fmac_f32_e32 v12, v108, v108
	v_fmac_f32_e32 v13, v109, v109
	v_fmac_f32_e32 v12, v110, v110
	v_fmac_f32_e32 v13, v111, v111
	v_add_f32_e32 v12, v12, v13
	s_nop 0
	s_nop 0
	v_add_f32_dpp v12, v12, v12 quad_perm:[1,0,3,2] row_mask:0xf bank_mask:0xf
	s_nop 0
	s_nop 0
	v_add_f32_dpp v12, v12, v12 quad_perm:[2,3,0,1] row_mask:0xf bank_mask:0xf
	s_nop 0
	s_nop 0
	v_add_f32_dpp v12, v12, v12 row_half_mirror row_mask:0xf bank_mask:0xf
	s_nop 0
	s_nop 0
	v_add_f32_dpp v12, v12, v12 row_mirror row_mask:0xf bank_mask:0xf
	v_mov_b32_e32 v13, v12
	s_nop 0
	s_nop 0
	v_permlane16_swap_b32_e32 v12, v13
	v_add_f32_e32 v12, v12, v13
	v_mov_b32_e32 v13, v12
	s_nop 0
	s_nop 0
	v_permlane32_swap_b32_e32 v12, v13
	v_add_f32_e32 v12, v12, v13
	v_fmamk_f32 v12, v12, 0x3a800000, v11
	v_rsq_f32_e32 v10, v12
	s_nop 0
	v_mul_f32_e32 v96, v96, v10
	v_mul_f32_e32 v97, v97, v10
	v_mul_f32_e32 v98, v98, v10
	v_mul_f32_e32 v99, v99, v10
	v_mul_f32_e32 v100, v100, v10
	v_mul_f32_e32 v101, v101, v10
	v_mul_f32_e32 v102, v102, v10
	v_mul_f32_e32 v103, v103, v10
	v_mul_f32_e32 v104, v104, v10
	v_mul_f32_e32 v105, v105, v10
	v_mul_f32_e32 v106, v106, v10
	v_mul_f32_e32 v107, v107, v10
	v_mul_f32_e32 v108, v108, v10
	v_mul_f32_e32 v109, v109, v10
	v_mul_f32_e32 v110, v110, v10
	v_mul_f32_e32 v111, v111, v10
	v_mul_f32_e32 v96, v96, v146
	v_mul_f32_e32 v97, v97, v147
	v_mul_f32_e32 v98, v98, v148
	v_mul_f32_e32 v99, v99, v149
	v_mul_f32_e32 v100, v100, v150
	v_mul_f32_e32 v101, v101, v151
	v_mul_f32_e32 v102, v102, v152
	v_mul_f32_e32 v103, v103, v153
	v_mul_f32_e32 v104, v104, v154
	v_mul_f32_e32 v105, v105, v155
	v_mul_f32_e32 v106, v106, v156
	v_mul_f32_e32 v107, v107, v157
	v_mul_f32_e32 v108, v108, v158
	v_mul_f32_e32 v109, v109, v159
	v_mul_f32_e32 v110, v110, v160
	v_mul_f32_e32 v111, v111, v161
	v_fma_f32 v96, v96, v194, v210
	v_fma_f32 v97, v97, v195, v211
	v_fma_f32 v98, v98, v196, v212
	v_fma_f32 v99, v99, v197, v213
	v_fma_f32 v100, v100, v198, v214
	v_fma_f32 v101, v101, v199, v215
	v_fma_f32 v102, v102, v200, v216
	v_fma_f32 v103, v103, v201, v217
	v_fma_f32 v104, v104, v202, v218
	v_fma_f32 v105, v105, v203, v219
	v_fma_f32 v106, v106, v204, v220
	v_fma_f32 v107, v107, v205, v221
	v_fma_f32 v108, v108, v206, v222
	v_fma_f32 v109, v109, v207, v223
	v_fma_f32 v110, v110, v208, v224
	v_fma_f32 v111, v111, v209, v225
	v_cvt_pk_bf16_f32 v226, v96, v97
	v_cvt_pk_bf16_f32 v227, v98, v99
	v_cvt_pk_bf16_f32 v228, v100, v101
	v_cvt_pk_bf16_f32 v229, v102, v103
	v_cvt_pk_bf16_f32 v230, v104, v105
	v_cvt_pk_bf16_f32 v231, v106, v107
	v_cvt_pk_bf16_f32 v232, v108, v109
	v_cvt_pk_bf16_f32 v233, v110, v111
	global_store_dwordx2 v3, v[226:227], s[10:11]
	global_store_dwordx2 v4, v[228:229], s[10:11]
	global_store_dwordx2 v5, v[230:231], s[10:11]
	global_store_dwordx2 v6, v[232:233], s[10:11]
	s_add_u32 s10, s10, 0x40000
	s_addc_u32 s11, s11, 0
	s_nop 0
	s_waitcnt vmcnt(28)
	v_mul_f32_e32 v12, v112, v112
	v_mul_f32_e32 v13, v113, v113
	v_fmac_f32_e32 v12, v114, v114
	v_fmac_f32_e32 v13, v115, v115
	v_fmac_f32_e32 v12, v116, v116
	v_fmac_f32_e32 v13, v117, v117
	v_fmac_f32_e32 v12, v118, v118
	v_fmac_f32_e32 v13, v119, v119
	v_fmac_f32_e32 v12, v120, v120
	v_fmac_f32_e32 v13, v121, v121
	v_fmac_f32_e32 v12, v122, v122
	v_fmac_f32_e32 v13, v123, v123
	v_fmac_f32_e32 v12, v124, v124
	v_fmac_f32_e32 v13, v125, v125
	v_fmac_f32_e32 v12, v126, v126
	v_fmac_f32_e32 v13, v127, v127
	v_add_f32_e32 v12, v12, v13
	s_nop 0
	s_nop 0
	v_add_f32_dpp v12, v12, v12 quad_perm:[1,0,3,2] row_mask:0xf bank_mask:0xf
	s_nop 0
	s_nop 0
	v_add_f32_dpp v12, v12, v12 quad_perm:[2,3,0,1] row_mask:0xf bank_mask:0xf
	s_nop 0
	s_nop 0
	v_add_f32_dpp v12, v12, v12 row_half_mirror row_mask:0xf bank_mask:0xf
	s_nop 0
	s_nop 0
	v_add_f32_dpp v12, v12, v12 row_mirror row_mask:0xf bank_mask:0xf
	v_mov_b32_e32 v13, v12
	s_nop 0
	s_nop 0
	v_permlane16_swap_b32_e32 v12, v13
	v_add_f32_e32 v12, v12, v13
	v_mov_b32_e32 v13, v12
	s_nop 0
	s_nop 0
	v_permlane32_swap_b32_e32 v12, v13
	v_add_f32_e32 v12, v12, v13
	v_fmamk_f32 v12, v12, 0x3a800000, v11
	v_rsq_f32_e32 v10, v12
	s_nop 0
	v_mul_f32_e32 v112, v112, v10
	v_mul_f32_e32 v113, v113, v10
	v_mul_f32_e32 v114, v114, v10
	v_mul_f32_e32 v115, v115, v10
	v_mul_f32_e32 v116, v116, v10
	v_mul_f32_e32 v117, v117, v10
	v_mul_f32_e32 v118, v118, v10
	v_mul_f32_e32 v119, v119, v10
	v_mul_f32_e32 v120, v120, v10
	v_mul_f32_e32 v121, v121, v10
	v_mul_f32_e32 v122, v122, v10
	v_mul_f32_e32 v123, v123, v10
	v_mul_f32_e32 v124, v124, v10
	v_mul_f32_e32 v125, v125, v10
	v_mul_f32_e32 v126, v126, v10
	v_mul_f32_e32 v127, v127, v10
	v_mul_f32_e32 v112, v112, v146
	v_mul_f32_e32 v113, v113, v147
	v_mul_f32_e32 v114, v114, v148
	v_mul_f32_e32 v115, v115, v149
	v_mul_f32_e32 v116, v116, v150
	v_mul_f32_e32 v117, v117, v151
	v_mul_f32_e32 v118, v118, v152
	v_mul_f32_e32 v119, v119, v153
	v_mul_f32_e32 v120, v120, v154
	v_mul_f32_e32 v121, v121, v155
	v_mul_f32_e32 v122, v122, v156
	v_mul_f32_e32 v123, v123, v157
	v_mul_f32_e32 v124, v124, v158
	v_mul_f32_e32 v125, v125, v159
	v_mul_f32_e32 v126, v126, v160
	v_mul_f32_e32 v127, v127, v161
	v_fma_f32 v112, v112, v194, v210
	v_fma_f32 v113, v113, v195, v211
	v_fma_f32 v114, v114, v196, v212
	v_fma_f32 v115, v115, v197, v213
	v_fma_f32 v116, v116, v198, v214
	v_fma_f32 v117, v117, v199, v215
	v_fma_f32 v118, v118, v200, v216
	v_fma_f32 v119, v119, v201, v217
	v_fma_f32 v120, v120, v202, v218
	v_fma_f32 v121, v121, v203, v219
	v_fma_f32 v122, v122, v204, v220
	v_fma_f32 v123, v123, v205, v221
	v_fma_f32 v124, v124, v206, v222
	v_fma_f32 v125, v125, v207, v223
	v_fma_f32 v126, v126, v208, v224
	v_fma_f32 v127, v127, v209, v225
	v_cvt_pk_bf16_f32 v226, v112, v113
	v_cvt_pk_bf16_f32 v227, v114, v115
	v_cvt_pk_bf16_f32 v228, v116, v117
	v_cvt_pk_bf16_f32 v229, v118, v119
	v_cvt_pk_bf16_f32 v230, v120, v121
	v_cvt_pk_bf16_f32 v231, v122, v123
	v_cvt_pk_bf16_f32 v232, v124, v125
	v_cvt_pk_bf16_f32 v233, v126, v127
	global_store_dwordx2 v3, v[226:227], s[10:11]
	global_store_dwordx2 v4, v[228:229], s[10:11]
	global_store_dwordx2 v5, v[230:231], s[10:11]
	global_store_dwordx2 v6, v[232:233], s[10:11]
	s_add_u32 s10, s10, 0x40000
	s_addc_u32 s11, s11, 0
	s_nop 0
	s_waitcnt vmcnt(28)
	v_mul_f32_e32 v12, v128, v128
	v_mul_f32_e32 v13, v129, v129
	v_fmac_f32_e32 v12, v130, v130
	v_fmac_f32_e32 v13, v131, v131
	v_fmac_f32_e32 v12, v132, v132
	v_fmac_f32_e32 v13, v133, v133
	v_fmac_f32_e32 v12, v134, v134
	v_fmac_f32_e32 v13, v135, v135
	v_fmac_f32_e32 v12, v136, v136
	v_fmac_f32_e32 v13, v137, v137
	v_fmac_f32_e32 v12, v138, v138
	v_fmac_f32_e32 v13, v139, v139
	v_fmac_f32_e32 v12, v140, v140
	v_fmac_f32_e32 v13, v141, v141
	v_fmac_f32_e32 v12, v142, v142
	v_fmac_f32_e32 v13, v143, v143
	v_add_f32_e32 v12, v12, v13
	s_nop 0
	s_nop 0
	v_add_f32_dpp v12, v12, v12 quad_perm:[1,0,3,2] row_mask:0xf bank_mask:0xf
	s_nop 0
	s_nop 0
	v_add_f32_dpp v12, v12, v12 quad_perm:[2,3,0,1] row_mask:0xf bank_mask:0xf
	s_nop 0
	s_nop 0
	v_add_f32_dpp v12, v12, v12 row_half_mirror row_mask:0xf bank_mask:0xf
	s_nop 0
	s_nop 0
	v_add_f32_dpp v12, v12, v12 row_mirror row_mask:0xf bank_mask:0xf
	v_mov_b32_e32 v13, v12
	s_nop 0
	s_nop 0
	v_permlane16_swap_b32_e32 v12, v13
	v_add_f32_e32 v12, v12, v13
	v_mov_b32_e32 v13, v12
	s_nop 0
	s_nop 0
	v_permlane32_swap_b32_e32 v12, v13
	v_add_f32_e32 v12, v12, v13
	v_fmamk_f32 v12, v12, 0x3a800000, v11
	v_rsq_f32_e32 v10, v12
	s_nop 0
	v_mul_f32_e32 v128, v128, v10
	v_mul_f32_e32 v129, v129, v10
	v_mul_f32_e32 v130, v130, v10
	v_mul_f32_e32 v131, v131, v10
	v_mul_f32_e32 v132, v132, v10
	v_mul_f32_e32 v133, v133, v10
	v_mul_f32_e32 v134, v134, v10
	v_mul_f32_e32 v135, v135, v10
	v_mul_f32_e32 v136, v136, v10
	v_mul_f32_e32 v137, v137, v10
	v_mul_f32_e32 v138, v138, v10
	v_mul_f32_e32 v139, v139, v10
	v_mul_f32_e32 v140, v140, v10
	v_mul_f32_e32 v141, v141, v10
	v_mul_f32_e32 v142, v142, v10
	v_mul_f32_e32 v143, v143, v10
	v_mul_f32_e32 v128, v128, v146
	v_mul_f32_e32 v129, v129, v147
	v_mul_f32_e32 v130, v130, v148
	v_mul_f32_e32 v131, v131, v149
	v_mul_f32_e32 v132, v132, v150
	v_mul_f32_e32 v133, v133, v151
	v_mul_f32_e32 v134, v134, v152
	v_mul_f32_e32 v135, v135, v153
	v_mul_f32_e32 v136, v136, v154
	v_mul_f32_e32 v137, v137, v155
	v_mul_f32_e32 v138, v138, v156
	v_mul_f32_e32 v139, v139, v157
	v_mul_f32_e32 v140, v140, v158
	v_mul_f32_e32 v141, v141, v159
	v_mul_f32_e32 v142, v142, v160
	v_mul_f32_e32 v143, v143, v161
	v_fma_f32 v128, v128, v194, v210
	v_fma_f32 v129, v129, v195, v211
	v_fma_f32 v130, v130, v196, v212
	v_fma_f32 v131, v131, v197, v213
	v_fma_f32 v132, v132, v198, v214
	v_fma_f32 v133, v133, v199, v215
	v_fma_f32 v134, v134, v200, v216
	v_fma_f32 v135, v135, v201, v217
	v_fma_f32 v136, v136, v202, v218
	v_fma_f32 v137, v137, v203, v219
	v_fma_f32 v138, v138, v204, v220
	v_fma_f32 v139, v139, v205, v221
	v_fma_f32 v140, v140, v206, v222
	v_fma_f32 v141, v141, v207, v223
	v_fma_f32 v142, v142, v208, v224
	v_fma_f32 v143, v143, v209, v225
	v_cvt_pk_bf16_f32 v226, v128, v129
	v_cvt_pk_bf16_f32 v227, v130, v131
	v_cvt_pk_bf16_f32 v228, v132, v133
	v_cvt_pk_bf16_f32 v229, v134, v135
	v_cvt_pk_bf16_f32 v230, v136, v137
	v_cvt_pk_bf16_f32 v231, v138, v139
	v_cvt_pk_bf16_f32 v232, v140, v141
	v_cvt_pk_bf16_f32 v233, v142, v143
	global_store_dwordx2 v3, v[226:227], s[10:11]
	global_store_dwordx2 v4, v[228:229], s[10:11]
	global_store_dwordx2 v5, v[230:231], s[10:11]
	global_store_dwordx2 v6, v[232:233], s[10:11]
	s_nop 0
